# add A2 and gate_unit LDS-fragment prefetch (double-buffered ds_read_tr ahead of MFMA chains) on top of load hoists
# baseline (speedup 1.0000x reference)
.LBB0_903:
	s_load_dwordx4 s[4:7], s[0:1], 0x60
	s_load_dwordx2 s[12:13], s[0:1], 0x78
	s_and_b32 s11, s63, 3
	s_lshl_b64 s[16:17], s[72:73], 2
	v_ashrrev_i32_e32 v44, 2, v188
	s_waitcnt lgkmcnt(0)
	s_add_u32 s4, s4, s16
	s_addc_u32 s5, s5, s17
	s_lshl_b32 s18, s11, 9
	s_add_u32 s8, s4, s18
	s_addc_u32 s9, s5, 0
	s_add_u32 s4, s6, s16
	s_addc_u32 s5, s7, s17
	s_add_u32 s6, s4, s18
	s_addc_u32 s7, s5, 0
	s_add_u32 s4, s12, s16
	v_add_u32_e32 v2, s10, v44
	s_addc_u32 s5, s13, s17
	v_ashrrev_i32_e32 v3, 31, v2
	s_add_u32 s4, s4, s18
	v_lshlrev_b32_e32 v0, 5, v188
	v_lshl_add_u64 v[4:5], v[2:3], 3, s[84:85]
	v_lshlrev_b64 v[2:3], 13, v[2:3]
	s_addc_u32 s5, s5, 0
	v_and_b32_e32 v18, 0x60, v0
	v_lshl_add_u64 v[2:3], s[82:83], 0, v[2:3]
	s_lshl_b32 s40, s11, 8
	v_lshl_add_u64 v[2:3], v[2:3], 0, s[40:41]
	v_lshlrev_b32_e32 v0, 1, v18
	v_lshl_add_u64 v[2:3], v[2:3], 0, v[0:1]
	s_mov_b64 s[12:13], 0x1000
	global_load_dwordx2 v[42:43], v[4:5], off
	v_lshl_add_u64 v[14:15], v[2:3], 0, s[12:13]
	v_add_co_u32_e32 v2, vcc, s44, v2
	v_lshlrev_b32_e32 v56, 2, v18
	s_nop 0
	v_addc_co_u32_e32 v3, vcc, 0, v3, vcc
	global_load_dwordx4 v[10:13], v[2:3], off
	s_nop 0
	global_load_dwordx4 v[2:5], v[14:15], off offset:48
	global_load_dwordx4 v[6:9], v[14:15], off offset:32
	s_nop 0
	global_load_dwordx4 v[14:17], v[14:15], off offset:16
	s_nop 0
	global_load_dwordx4 v[18:21], v56, s[8:9] offset:48
	global_load_dwordx4 v[22:25], v56, s[8:9] offset:32
	global_load_dwordx4 v[26:29], v56, s[8:9] offset:16
	global_load_dwordx4 v[30:33], v56, s[8:9]
	global_load_dwordx4 v[34:37], v56, s[6:7] offset:48
	global_load_dwordx4 v[38:41], v56, s[6:7] offset:32
	global_load_dwordx4 v[46:49], v56, s[6:7] offset:16
	global_load_dwordx4 v[50:53], v56, s[6:7]
	v_mul_lo_u32 v45, v44, s46
	v_add3_u32 v0, 0, v45, v0
	s_waitcnt vmcnt(11)
	v_lshlrev_b32_e32 v54, 16, v10
	v_and_b32_e32 v55, 0xffff0000, v10
	v_pk_add_f32 v[54:55], v[54:55], v[42:43] op_sel_hi:[1,0] neg_lo:[0,1] neg_hi:[0,1]
	s_nop 0
	v_pk_mul_f32 v[54:55], v[42:43], v[54:55] op_sel:[1,0]
	s_waitcnt vmcnt(0)
	v_pk_fma_f32 v[30:31], v[30:31], v[54:55], v[50:51]
	s_nop 0
	v_cvt_pk_bf16_f32 v10, v30, v31
	v_lshlrev_b32_e32 v30, 16, v11
	v_and_b32_e32 v31, 0xffff0000, v11
	v_pk_add_f32 v[30:31], v[30:31], v[42:43] op_sel_hi:[1,0] neg_lo:[0,1] neg_hi:[0,1]
	s_nop 0
	v_pk_mul_f32 v[30:31], v[42:43], v[30:31] op_sel:[1,0]
	s_nop 0
	v_pk_fma_f32 v[30:31], v[32:33], v[30:31], v[52:53]
	s_nop 0
	v_cvt_pk_bf16_f32 v11, v30, v31
	v_lshlrev_b32_e32 v30, 16, v12
	v_and_b32_e32 v31, 0xffff0000, v12
	v_pk_add_f32 v[30:31], v[30:31], v[42:43] op_sel_hi:[1,0] neg_lo:[0,1] neg_hi:[0,1]
	s_nop 0
	v_pk_mul_f32 v[30:31], v[42:43], v[30:31] op_sel:[1,0]
	s_nop 0
	v_pk_fma_f32 v[26:27], v[26:27], v[30:31], v[46:47]
	v_lshlrev_b32_e32 v46, 16, v6
	v_cvt_pk_bf16_f32 v12, v26, v27
	v_lshlrev_b32_e32 v26, 16, v13
	v_and_b32_e32 v27, 0xffff0000, v13
	v_pk_add_f32 v[26:27], v[26:27], v[42:43] op_sel_hi:[1,0] neg_lo:[0,1] neg_hi:[0,1]
	v_and_b32_e32 v47, 0xffff0000, v6
	v_pk_mul_f32 v[26:27], v[42:43], v[26:27] op_sel:[1,0]
	v_pk_add_f32 v[46:47], v[46:47], v[42:43] op_sel_hi:[1,0] neg_lo:[0,1] neg_hi:[0,1]
	v_pk_fma_f32 v[26:27], v[28:29], v[26:27], v[48:49]
	v_pk_mul_f32 v[46:47], v[42:43], v[46:47] op_sel:[1,0]
	v_cvt_pk_bf16_f32 v13, v26, v27
	ds_write_b128 v0, v[10:13]
	v_lshlrev_b32_e32 v10, 16, v14
	v_and_b32_e32 v11, 0xffff0000, v14
	v_lshlrev_b32_e32 v12, 16, v15
	v_and_b32_e32 v13, 0xffff0000, v15
	v_pk_add_f32 v[10:11], v[10:11], v[42:43] op_sel_hi:[1,0] neg_lo:[0,1] neg_hi:[0,1]
	v_pk_add_f32 v[12:13], v[12:13], v[42:43] op_sel_hi:[1,0] neg_lo:[0,1] neg_hi:[0,1]
	v_pk_mul_f32 v[10:11], v[42:43], v[10:11] op_sel:[1,0]
	v_pk_mul_f32 v[12:13], v[42:43], v[12:13] op_sel:[1,0]
	v_pk_fma_f32 v[10:11], v[22:23], v[10:11], v[38:39]
	v_pk_fma_f32 v[12:13], v[24:25], v[12:13], v[40:41]
	v_cvt_pk_bf16_f32 v10, v10, v11
	v_cvt_pk_bf16_f32 v11, v12, v13
	v_lshlrev_b32_e32 v12, 16, v16
	v_and_b32_e32 v13, 0xffff0000, v16
	v_lshlrev_b32_e32 v14, 16, v17
	v_and_b32_e32 v15, 0xffff0000, v17
	v_pk_add_f32 v[12:13], v[12:13], v[42:43] op_sel_hi:[1,0] neg_lo:[0,1] neg_hi:[0,1]
	v_pk_add_f32 v[14:15], v[14:15], v[42:43] op_sel_hi:[1,0] neg_lo:[0,1] neg_hi:[0,1]
	v_pk_mul_f32 v[12:13], v[42:43], v[12:13] op_sel:[1,0]
	v_pk_mul_f32 v[14:15], v[42:43], v[14:15] op_sel:[1,0]
	v_pk_fma_f32 v[12:13], v[18:19], v[12:13], v[34:35]
	v_pk_fma_f32 v[14:15], v[20:21], v[14:15], v[36:37]
	v_cvt_pk_bf16_f32 v12, v12, v13
	v_cvt_pk_bf16_f32 v13, v14, v15
	ds_write_b128 v0, v[10:13] offset:16
	global_load_dwordx4 v[10:13], v56, s[8:9] offset:112
	global_load_dwordx4 v[18:21], v56, s[8:9] offset:96
	global_load_dwordx4 v[26:29], v56, s[8:9] offset:80
	global_load_dwordx4 v[34:37], v56, s[8:9] offset:64
	global_load_dwordx4 v[14:17], v56, s[6:7] offset:112
	global_load_dwordx4 v[22:25], v56, s[6:7] offset:96
	global_load_dwordx4 v[30:33], v56, s[6:7] offset:80
	global_load_dwordx4 v[38:41], v56, s[6:7] offset:64
	s_lshl_b32 s6, s11, 15
	v_readlane_b32 s7, v255, 33
	s_add_u32 s6, s7, s6
	v_readlane_b32 s7, v255, 34
	s_addc_u32 s7, s7, 0
	s_mov_b32 s8, 4
	s_waitcnt vmcnt(0)
	v_pk_fma_f32 v[34:35], v[34:35], v[46:47], v[38:39]
	s_nop 0
	v_cvt_pk_bf16_f32 v6, v34, v35
	v_lshlrev_b32_e32 v34, 16, v7
	v_and_b32_e32 v35, 0xffff0000, v7
	v_pk_add_f32 v[34:35], v[34:35], v[42:43] op_sel_hi:[1,0] neg_lo:[0,1] neg_hi:[0,1]
	s_nop 0
	v_pk_mul_f32 v[34:35], v[42:43], v[34:35] op_sel:[1,0]
	s_nop 0
	v_pk_fma_f32 v[34:35], v[36:37], v[34:35], v[40:41]
	s_nop 0
	v_cvt_pk_bf16_f32 v7, v34, v35
	v_lshlrev_b32_e32 v34, 16, v8
	v_and_b32_e32 v35, 0xffff0000, v8
	v_pk_add_f32 v[34:35], v[34:35], v[42:43] op_sel_hi:[1,0] neg_lo:[0,1] neg_hi:[0,1]
	s_nop 0
	v_pk_mul_f32 v[34:35], v[42:43], v[34:35] op_sel:[1,0]
	s_nop 0
	v_pk_fma_f32 v[26:27], v[26:27], v[34:35], v[30:31]
	s_nop 0
	v_cvt_pk_bf16_f32 v8, v26, v27
	v_lshlrev_b32_e32 v26, 16, v9
	v_and_b32_e32 v27, 0xffff0000, v9
	v_pk_add_f32 v[26:27], v[26:27], v[42:43] op_sel_hi:[1,0] neg_lo:[0,1] neg_hi:[0,1]
	s_nop 0
	v_pk_mul_f32 v[26:27], v[42:43], v[26:27] op_sel:[1,0]
	s_nop 0
	v_pk_fma_f32 v[26:27], v[28:29], v[26:27], v[32:33]
	s_nop 0
	v_cvt_pk_bf16_f32 v9, v26, v27
	ds_write_b128 v0, v[6:9] offset:32
	v_lshlrev_b32_e32 v6, 16, v2
	v_and_b32_e32 v7, 0xffff0000, v2
	v_pk_add_f32 v[6:7], v[6:7], v[42:43] op_sel_hi:[1,0] neg_lo:[0,1] neg_hi:[0,1]
	s_nop 0
	v_pk_mul_f32 v[6:7], v[42:43], v[6:7] op_sel:[1,0]
	s_nop 0
	v_pk_fma_f32 v[6:7], v[18:19], v[6:7], v[22:23]
	v_bfi_b32 v18, -16, v44, v188
	v_cvt_pk_bf16_f32 v2, v6, v7
	v_lshlrev_b32_e32 v6, 16, v3
	v_and_b32_e32 v7, 0xffff0000, v3
	v_pk_add_f32 v[6:7], v[6:7], v[42:43] op_sel_hi:[1,0] neg_lo:[0,1] neg_hi:[0,1]
	v_ashrrev_i32_e32 v19, 31, v18
	v_pk_mul_f32 v[6:7], v[42:43], v[6:7] op_sel:[1,0]
	s_nop 0
	v_pk_fma_f32 v[6:7], v[20:21], v[6:7], v[24:25]
	v_add_u32_e32 v20, s10, v18
	v_cvt_pk_bf16_f32 v3, v6, v7
	v_lshlrev_b32_e32 v6, 16, v4
	v_and_b32_e32 v7, 0xffff0000, v4
	v_pk_add_f32 v[6:7], v[6:7], v[42:43] op_sel_hi:[1,0] neg_lo:[0,1] neg_hi:[0,1]
	v_ashrrev_i32_e32 v21, 31, v20
	v_pk_mul_f32 v[6:7], v[42:43], v[6:7] op_sel:[1,0]
	s_nop 0
	v_pk_fma_f32 v[6:7], v[10:11], v[6:7], v[14:15]
	s_nop 0
	v_cvt_pk_bf16_f32 v4, v6, v7
	v_lshlrev_b32_e32 v6, 16, v5
	v_and_b32_e32 v7, 0xffff0000, v5
	v_pk_add_f32 v[6:7], v[6:7], v[42:43] op_sel_hi:[1,0] neg_lo:[0,1] neg_hi:[0,1]
	s_nop 0
	v_pk_mul_f32 v[6:7], v[42:43], v[6:7] op_sel:[1,0]
	s_nop 0
	v_pk_fma_f32 v[6:7], v[12:13], v[6:7], v[16:17]
	s_nop 0
	v_cvt_pk_bf16_f32 v5, v6, v7
	ds_write_b128 v0, v[2:5] offset:48
	v_bfe_u32 v0, v188, 4, 2
	v_lshlrev_b64 v[2:3], 8, v[18:19]
	v_lshl_add_u64 v[2:3], s[6:7], 0, v[2:3]
	v_lshlrev_b32_e32 v32, 3, v0
	v_lshlrev_b32_e32 v0, 4, v0
	v_lshl_add_u64 v[10:11], v[2:3], 0, v[0:1]
	global_load_dwordx4 v[2:5], v[10:11], off
	global_load_dwordx4 v[6:9], v[10:11], off offset:64
	global_load_dwordx4 v[14:17], v[10:11], off offset:128
	s_nop 0
	global_load_dwordx4 v[10:13], v[10:11], off offset:192
	v_lshl_add_u64 v[18:19], v[18:19], 2, s[4:5]
	v_bfe_u32 v0, v188, 2, 2
	global_load_dword v22, v[18:19], off
	v_lshlrev_b64 v[76:77], 13, v[20:21]
	v_lshl_add_u64 v[76:77], s[82:83], 0, v[76:77]
	v_or_b32_e32 v78, s40, v32
	v_mov_b32_e32 v79, 0
	v_lshl_add_u64 v[76:77], v[76:77], 0, v[78:79]
	global_load_dwordx2 v[60:61], v[76:77], off offset:3072
	global_load_dwordx2 v[62:63], v[76:77], off offset:3104
	global_load_dwordx2 v[64:65], v[76:77], off offset:3136
	global_load_dwordx2 v[66:67], v[76:77], off offset:3168
	global_load_dwordx2 v[68:69], v[76:77], off offset:3200
	global_load_dwordx2 v[70:71], v[76:77], off offset:3232
	global_load_dwordx2 v[72:73], v[76:77], off offset:3264
	global_load_dwordx2 v[74:75], v[76:77], off offset:3296
	v_or_b32_e32 v0, v32, v0
	v_lshlrev_b32_e32 v18, 3, v188
	v_and_b32_e32 v23, 24, v18
	v_lshlrev_b64 v[18:19], 13, v[20:21]
	v_mul_u32_u24_e32 v0, 0x110, v0
	s_waitcnt lgkmcnt(0)
	s_barrier
	v_lshl_add_u64 v[28:29], s[82:83], 0, v[18:19]
	v_lshlrev_b64 v[18:19], 10, v[20:21]
	v_add3_u32 v23, 0, v23, v0
	v_lshl_add_u64 v[30:31], s[86:87], 0, v[18:19]
	ds_read_b64_tr_b16 v[80:81], v23
	ds_read_b64_tr_b16 v[82:83], v23 offset:1088
	ds_read_b64_tr_b16 v[84:85], v23 offset:8704
	ds_read_b64_tr_b16 v[86:87], v23 offset:9792
	ds_read_b64_tr_b16 v[88:89], v23 offset:17408
	ds_read_b64_tr_b16 v[90:91], v23 offset:18496
	ds_read_b64_tr_b16 v[92:93], v23 offset:26112
	ds_read_b64_tr_b16 v[94:95], v23 offset:27200
	v_or_b32_e32 v0, s40, v32
	s_waitcnt vmcnt(12) lgkmcnt(6)
	v_mfma_f32_16x16x32_bf16 v[18:21], v[80:83], v[2:5], 0
	s_waitcnt vmcnt(11) lgkmcnt(4)
	v_mfma_f32_16x16x32_bf16 v[18:21], v[84:87], v[6:9], v[18:21]
	s_waitcnt vmcnt(10) lgkmcnt(2)
	v_mfma_f32_16x16x32_bf16 v[18:21], v[88:91], v[14:17], v[18:21]
	s_waitcnt vmcnt(9) lgkmcnt(0)
	v_mfma_f32_16x16x32_bf16 v[18:21], v[92:95], v[10:13], v[18:21]
	ds_read_b64_tr_b16 v[96:97], v23 offset:32
	ds_read_b64_tr_b16 v[98:99], v23 offset:1120
	ds_read_b64_tr_b16 v[100:101], v23 offset:8736
	ds_read_b64_tr_b16 v[102:103], v23 offset:9824
	ds_read_b64_tr_b16 v[104:105], v23 offset:17440
	ds_read_b64_tr_b16 v[106:107], v23 offset:18528
	ds_read_b64_tr_b16 v[108:109], v23 offset:26144
	ds_read_b64_tr_b16 v[110:111], v23 offset:27232
	v_lshl_add_u64 v[26:27], v[28:29], 0, v[0:1]
	s_nop 0
	s_waitcnt vmcnt(7)
	v_lshlrev_b32_e32 v28, 16, v60
	v_and_b32_e32 v29, 0xffff0000, v60
	s_nop 2
	v_pk_add_f32 v[18:19], v[22:23], v[18:19] op_sel_hi:[0,1]
	v_lshlrev_b32_e32 v24, 16, v61
	v_and_b32_e32 v25, 0xffff0000, v61
	v_pk_add_f32 v[20:21], v[22:23], v[20:21] op_sel_hi:[0,1]
	v_pk_mul_f32 v[18:19], v[18:19], v[28:29]
	v_pk_mul_f32 v[20:21], v[20:21], v[24:25]
	v_cvt_pk_bf16_f32 v18, v18, v19
	v_cvt_pk_bf16_f32 v19, v20, v21
	v_lshl_add_u64 v[24:25], v[30:31], 0, v[0:1]
	global_store_dwordx2 v[24:25], v[18:19], off
	s_waitcnt lgkmcnt(6)
	v_mfma_f32_16x16x32_bf16 v[18:21], v[96:99], v[2:5], 0
	s_waitcnt lgkmcnt(4)
	v_mfma_f32_16x16x32_bf16 v[18:21], v[100:103], v[6:9], v[18:21]
	s_waitcnt lgkmcnt(2)
	v_mfma_f32_16x16x32_bf16 v[18:21], v[104:107], v[14:17], v[18:21]
	s_waitcnt lgkmcnt(0)
	v_mfma_f32_16x16x32_bf16 v[18:21], v[108:111], v[10:13], v[18:21]
	ds_read_b64_tr_b16 v[80:81], v23 offset:64
	ds_read_b64_tr_b16 v[82:83], v23 offset:1152
	ds_read_b64_tr_b16 v[84:85], v23 offset:8768
	ds_read_b64_tr_b16 v[86:87], v23 offset:9856
	ds_read_b64_tr_b16 v[88:89], v23 offset:17472
	ds_read_b64_tr_b16 v[90:91], v23 offset:18560
	ds_read_b64_tr_b16 v[92:93], v23 offset:26176
	ds_read_b64_tr_b16 v[94:95], v23 offset:27264
	s_nop 0
	s_waitcnt vmcnt(7)
	v_lshlrev_b32_e32 v30, 16, v62
	v_and_b32_e32 v31, 0xffff0000, v62
	s_nop 3
	v_pk_add_f32 v[18:19], v[22:23], v[18:19] op_sel_hi:[0,1]
	v_lshlrev_b32_e32 v28, 16, v63
	v_and_b32_e32 v29, 0xffff0000, v63
	v_pk_add_f32 v[20:21], v[22:23], v[20:21] op_sel_hi:[0,1]
	v_pk_mul_f32 v[18:19], v[18:19], v[30:31]
	v_pk_mul_f32 v[20:21], v[20:21], v[28:29]
	v_cvt_pk_bf16_f32 v18, v18, v19
	v_cvt_pk_bf16_f32 v19, v20, v21
	global_store_dwordx2 v[24:25], v[18:19], off offset:32
	s_waitcnt lgkmcnt(6)
	v_mfma_f32_16x16x32_bf16 v[18:21], v[80:83], v[2:5], 0
	s_waitcnt lgkmcnt(4)
	v_mfma_f32_16x16x32_bf16 v[18:21], v[84:87], v[6:9], v[18:21]
	s_waitcnt lgkmcnt(2)
	v_mfma_f32_16x16x32_bf16 v[18:21], v[88:91], v[14:17], v[18:21]
	s_waitcnt lgkmcnt(0)
	v_mfma_f32_16x16x32_bf16 v[18:21], v[92:95], v[10:13], v[18:21]
	ds_read_b64_tr_b16 v[96:97], v23 offset:96
	ds_read_b64_tr_b16 v[98:99], v23 offset:1184
	ds_read_b64_tr_b16 v[100:101], v23 offset:8800
	ds_read_b64_tr_b16 v[102:103], v23 offset:9888
	ds_read_b64_tr_b16 v[104:105], v23 offset:17504
	ds_read_b64_tr_b16 v[106:107], v23 offset:18592
	ds_read_b64_tr_b16 v[108:109], v23 offset:26208
	ds_read_b64_tr_b16 v[110:111], v23 offset:27296
	s_nop 0
	s_waitcnt vmcnt(7)
	v_lshlrev_b32_e32 v30, 16, v64
	v_and_b32_e32 v31, 0xffff0000, v64
	s_nop 3
	v_pk_add_f32 v[18:19], v[22:23], v[18:19] op_sel_hi:[0,1]
	v_lshlrev_b32_e32 v28, 16, v65
	v_and_b32_e32 v29, 0xffff0000, v65
	v_pk_add_f32 v[20:21], v[22:23], v[20:21] op_sel_hi:[0,1]
	v_pk_mul_f32 v[18:19], v[18:19], v[30:31]
	v_pk_mul_f32 v[20:21], v[20:21], v[28:29]
	v_cvt_pk_bf16_f32 v18, v18, v19
	v_cvt_pk_bf16_f32 v19, v20, v21
	global_store_dwordx2 v[24:25], v[18:19], off offset:64
	s_waitcnt lgkmcnt(6)
	v_mfma_f32_16x16x32_bf16 v[18:21], v[96:99], v[2:5], 0
	s_waitcnt lgkmcnt(4)
	v_mfma_f32_16x16x32_bf16 v[18:21], v[100:103], v[6:9], v[18:21]
	s_waitcnt lgkmcnt(2)
	v_mfma_f32_16x16x32_bf16 v[18:21], v[104:107], v[14:17], v[18:21]
	s_waitcnt lgkmcnt(0)
	v_mfma_f32_16x16x32_bf16 v[18:21], v[108:111], v[10:13], v[18:21]
	ds_read_b64_tr_b16 v[80:81], v23 offset:128
	ds_read_b64_tr_b16 v[82:83], v23 offset:1216
	ds_read_b64_tr_b16 v[84:85], v23 offset:8832
	ds_read_b64_tr_b16 v[86:87], v23 offset:9920
	ds_read_b64_tr_b16 v[88:89], v23 offset:17536
	ds_read_b64_tr_b16 v[90:91], v23 offset:18624
	ds_read_b64_tr_b16 v[92:93], v23 offset:26240
	ds_read_b64_tr_b16 v[94:95], v23 offset:27328
	s_nop 0
	s_waitcnt vmcnt(7)
	v_lshlrev_b32_e32 v30, 16, v66
	v_and_b32_e32 v31, 0xffff0000, v66
	s_nop 3
	v_pk_add_f32 v[18:19], v[22:23], v[18:19] op_sel_hi:[0,1]
	v_lshlrev_b32_e32 v28, 16, v67
	v_and_b32_e32 v29, 0xffff0000, v67
	v_pk_add_f32 v[20:21], v[22:23], v[20:21] op_sel_hi:[0,1]
	v_pk_mul_f32 v[18:19], v[18:19], v[30:31]
	v_pk_mul_f32 v[20:21], v[20:21], v[28:29]
	v_cvt_pk_bf16_f32 v18, v18, v19
	v_cvt_pk_bf16_f32 v19, v20, v21
	global_store_dwordx2 v[24:25], v[18:19], off offset:96
	s_waitcnt lgkmcnt(6)
	v_mfma_f32_16x16x32_bf16 v[18:21], v[80:83], v[2:5], 0
	s_waitcnt lgkmcnt(4)
	v_mfma_f32_16x16x32_bf16 v[18:21], v[84:87], v[6:9], v[18:21]
	s_waitcnt lgkmcnt(2)
	v_mfma_f32_16x16x32_bf16 v[18:21], v[88:91], v[14:17], v[18:21]
	s_waitcnt lgkmcnt(0)
	v_mfma_f32_16x16x32_bf16 v[18:21], v[92:95], v[10:13], v[18:21]
	ds_read_b64_tr_b16 v[96:97], v23 offset:160
	ds_read_b64_tr_b16 v[98:99], v23 offset:1248
	ds_read_b64_tr_b16 v[100:101], v23 offset:8864
	ds_read_b64_tr_b16 v[102:103], v23 offset:9952
	ds_read_b64_tr_b16 v[104:105], v23 offset:17568
	ds_read_b64_tr_b16 v[106:107], v23 offset:18656
	ds_read_b64_tr_b16 v[108:109], v23 offset:26272
	ds_read_b64_tr_b16 v[110:111], v23 offset:27360
	s_nop 0
	s_waitcnt vmcnt(7)
	v_lshlrev_b32_e32 v30, 16, v68
	v_and_b32_e32 v31, 0xffff0000, v68
	s_nop 3
	v_pk_add_f32 v[18:19], v[22:23], v[18:19] op_sel_hi:[0,1]
	v_lshlrev_b32_e32 v28, 16, v69
	v_and_b32_e32 v29, 0xffff0000, v69
	v_pk_add_f32 v[20:21], v[22:23], v[20:21] op_sel_hi:[0,1]
	v_pk_mul_f32 v[18:19], v[18:19], v[30:31]
	v_pk_mul_f32 v[20:21], v[20:21], v[28:29]
	v_cvt_pk_bf16_f32 v18, v18, v19
	v_cvt_pk_bf16_f32 v19, v20, v21
	global_store_dwordx2 v[24:25], v[18:19], off offset:128
	s_waitcnt lgkmcnt(6)
	v_mfma_f32_16x16x32_bf16 v[18:21], v[96:99], v[2:5], 0
	s_waitcnt lgkmcnt(4)
	v_mfma_f32_16x16x32_bf16 v[18:21], v[100:103], v[6:9], v[18:21]
	s_waitcnt lgkmcnt(2)
	v_mfma_f32_16x16x32_bf16 v[18:21], v[104:107], v[14:17], v[18:21]
	s_waitcnt lgkmcnt(0)
	v_mfma_f32_16x16x32_bf16 v[18:21], v[108:111], v[10:13], v[18:21]
	ds_read_b64_tr_b16 v[80:81], v23 offset:192
	ds_read_b64_tr_b16 v[82:83], v23 offset:1280
	ds_read_b64_tr_b16 v[84:85], v23 offset:8896
	ds_read_b64_tr_b16 v[86:87], v23 offset:9984
	ds_read_b64_tr_b16 v[88:89], v23 offset:17600
	ds_read_b64_tr_b16 v[90:91], v23 offset:18688
	ds_read_b64_tr_b16 v[92:93], v23 offset:26304
	ds_read_b64_tr_b16 v[94:95], v23 offset:27392
	s_nop 0
	s_waitcnt vmcnt(7)
	v_lshlrev_b32_e32 v30, 16, v70
	v_and_b32_e32 v31, 0xffff0000, v70
	s_nop 3
	v_pk_add_f32 v[18:19], v[22:23], v[18:19] op_sel_hi:[0,1]
	v_lshlrev_b32_e32 v28, 16, v71
	v_and_b32_e32 v29, 0xffff0000, v71
	v_pk_add_f32 v[20:21], v[22:23], v[20:21] op_sel_hi:[0,1]
	v_pk_mul_f32 v[18:19], v[18:19], v[30:31]
	v_pk_mul_f32 v[20:21], v[20:21], v[28:29]
	v_cvt_pk_bf16_f32 v18, v18, v19
	v_cvt_pk_bf16_f32 v19, v20, v21
	global_store_dwordx2 v[24:25], v[18:19], off offset:160
	s_waitcnt lgkmcnt(6)
	v_mfma_f32_16x16x32_bf16 v[18:21], v[80:83], v[2:5], 0
	s_waitcnt lgkmcnt(4)
	v_mfma_f32_16x16x32_bf16 v[18:21], v[84:87], v[6:9], v[18:21]
	s_waitcnt lgkmcnt(2)
	v_mfma_f32_16x16x32_bf16 v[18:21], v[88:91], v[14:17], v[18:21]
	s_waitcnt lgkmcnt(0)
	v_mfma_f32_16x16x32_bf16 v[18:21], v[92:95], v[10:13], v[18:21]
	s_nop 0
	s_waitcnt vmcnt(7)
	v_lshlrev_b32_e32 v30, 16, v72
	v_and_b32_e32 v31, 0xffff0000, v72
	s_nop 3
	v_pk_add_f32 v[18:19], v[22:23], v[18:19] op_sel_hi:[0,1]
	v_lshlrev_b32_e32 v28, 16, v73
	v_and_b32_e32 v29, 0xffff0000, v73
	v_pk_add_f32 v[20:21], v[22:23], v[20:21] op_sel_hi:[0,1]
	v_pk_mul_f32 v[18:19], v[18:19], v[30:31]
	v_pk_mul_f32 v[20:21], v[20:21], v[28:29]
	v_cvt_pk_bf16_f32 v18, v18, v19
	v_cvt_pk_bf16_f32 v19, v20, v21
	global_store_dwordx2 v[24:25], v[18:19], off offset:192
	ds_read_b64_tr_b16 v[18:19], v23 offset:224
	ds_read_b64_tr_b16 v[20:21], v23 offset:1312
	s_waitcnt lgkmcnt(0)
	v_mfma_f32_16x16x32_bf16 v[2:5], v[18:21], v[2:5], 0
	ds_read_b64_tr_b16 v[18:19], v23 offset:8928
	ds_read_b64_tr_b16 v[20:21], v23 offset:10016
	s_waitcnt lgkmcnt(0)
	v_mfma_f32_16x16x32_bf16 v[2:5], v[18:21], v[6:9], v[2:5]
	ds_read_b64_tr_b16 v[6:7], v23 offset:17632
	ds_read_b64_tr_b16 v[8:9], v23 offset:18720
	s_waitcnt lgkmcnt(0)
	v_mfma_f32_16x16x32_bf16 v[2:5], v[6:9], v[14:17], v[2:5]
	ds_read_b64_tr_b16 v[6:7], v23 offset:26336
	ds_read_b64_tr_b16 v[8:9], v23 offset:27424
	s_waitcnt lgkmcnt(0)
	v_mfma_f32_16x16x32_bf16 v[2:5], v[6:9], v[10:13], v[2:5]
	s_nop 0
	s_waitcnt vmcnt(7)
	v_lshlrev_b32_e32 v8, 16, v74
	v_and_b32_e32 v9, 0xffff0000, v74
	s_nop 3
	v_pk_add_f32 v[2:3], v[22:23], v[2:3] op_sel_hi:[0,1]
	v_lshlrev_b32_e32 v6, 16, v75
	v_and_b32_e32 v7, 0xffff0000, v75
	v_pk_add_f32 v[4:5], v[22:23], v[4:5] op_sel_hi:[0,1]
	v_pk_mul_f32 v[2:3], v[2:3], v[8:9]
	v_pk_mul_f32 v[4:5], v[4:5], v[6:7]
	v_cvt_pk_bf16_f32 v2, v2, v3
	v_cvt_pk_bf16_f32 v3, v4, v5
	global_store_dwordx2 v[24:25], v[2:3], off offset:224
	s_waitcnt lgkmcnt(0)
	s_barrier

.LBB0_921:
	s_or_b64 exec, exec, s[26:27]
	v_readlane_b32 s6, v255, 16
	s_waitcnt lgkmcnt(0)
	s_barrier
	v_mul_hi_i32 v111, v106, s55
	s_waitcnt vmcnt(16)
	v_cndmask_b32_e64 v135, 0, v90, s[4:5]
	v_mov_b32_e32 v98, s6
	v_readlane_b32 s6, v255, 17
	ds_read_b32 v102, v98
	v_lshlrev_b32_e32 v90, 2, v110
	v_mov_b32_e32 v98, s6
	v_readlane_b32 s6, v255, 18
	ds_read_b32 v101, v98
	v_readlane_b32 s8, v255, 20
	v_mov_b32_e32 v98, s6
	v_readlane_b32 s6, v255, 19
	ds_read_b32 v98, v98
	s_waitcnt vmcnt(12)
	v_cndmask_b32_e32 v144, 0, v96, vcc
	v_mov_b32_e32 v100, s6
	ds_read_b32 v113, v100
	v_lshl_add_u32 v100, v109, 2, s45
	ds_read_b32 v100, v100 offset:1536
	s_movk_i32 s6, 0xf700
	v_add_u32_e32 v96, s8, v90
	v_cndmask_b32_e64 v141, 0, v92, s[4:5]
	v_cndmask_b32_e64 v142, 0, v93, s[4:5]
	s_waitcnt lgkmcnt(0)
	v_pk_add_f32 v[104:105], v[102:103], v[100:101] op_sel_hi:[0,1]
	v_sub_f32_e32 v100, v104, v105
	v_mul_f32_e32 v100, 0x3fb8aa3b, v100
	v_exp_f32_e32 v104, v100
	v_sub_u32_e32 v100, 0x67f, v109
	v_lshl_add_u32 v100, v100, 2, s45
	ds_read_b32 v112, v100
	v_cndmask_b32_e32 v136, 0, v94, vcc
	v_cndmask_b32_e32 v143, 0, v95, vcc
	v_cndmask_b32_e32 v145, 0, v97, vcc
	v_lshlrev_b32_e32 v134, 16, v136
	s_waitcnt lgkmcnt(0)
	v_pk_add_f32 v[100:101], v[98:99], v[112:113] op_sel_hi:[0,1]
	v_lshrrev_b32_e32 v112, 31, v111
	v_ashrrev_i32_e32 v111, 9, v111
	v_add_u32_e32 v111, v111, v112
	v_mov_b32_e32 v112, 0xffffff00
	v_mad_i32_i24 v138, v111, s6, v106
	v_lshlrev_b32_e32 v139, 8, v111
	v_lshl_add_u32 v140, v111, 11, v112
	ds_read_b128 v[92:95], v96
	ds_read_b128 v[110:113], v96 offset:16
	ds_read_b128 v[114:117], v96 offset:1536
	ds_read_b128 v[118:121], v96 offset:1552
	ds_read_b128 v[122:125], v96 offset:3072
	ds_read_b128 v[126:129], v96 offset:3088
	v_lshlrev_b32_e32 v96, 16, v135
	v_and_b32_e32 v97, 0xffff0000, v135
	v_and_b32_e32 v135, 0xffff0000, v136
	v_lshlrev_b32_e32 v136, 16, v86
	v_and_b32_e32 v137, 0xffff0000, v86
	s_waitcnt lgkmcnt(3)
	v_pk_mul_f32 v[114:115], v[114:115], v[136:137]
	v_cndmask_b32_e64 v91, 0, v91, s[4:5]
	v_pk_fma_f32 v[92:93], v[92:93], v[96:97], v[114:115]
	v_lshlrev_b32_e32 v114, 16, v143
	s_waitcnt lgkmcnt(1)
	v_pk_fma_f32 v[92:93], v[122:123], v[134:135], v[92:93]
	v_and_b32_e32 v115, 0xffff0000, v143
	v_mul_f32_e32 v86, 0xbfb8aa3b, v92
	v_exp_f32_e32 v86, v86
	v_cmp_lt_i32_e64 s[6:7], s54, v138
	v_sub_f32_e32 v100, v100, v101
	v_mul_f32_e32 v100, 0x3fb8aa3b, v100
	v_add_f32_e32 v86, 1.0, v86
	v_rcp_f32_e32 v96, v86
	v_mul_f32_e32 v86, 0xbfb8aa3b, v93
	v_exp_f32_e32 v86, v86
	v_exp_f32_e32 v100, v100
	v_mul_lo_u32 v109, v109, s46
	s_waitcnt vmcnt(0)
	v_cndmask_b32_e32 v123, 0, v82, vcc
	v_add_f32_e32 v86, 1.0, v86
	v_rcp_f32_e32 v97, v86
	v_lshlrev_b32_e32 v86, 16, v87
	v_and_b32_e32 v87, 0xffff0000, v87
	v_pk_mul_f32 v[86:87], v[116:117], v[86:87]
	v_pk_mul_f32 v[96:97], v[92:93], v[96:97]
	v_lshlrev_b32_e32 v92, 16, v91
	v_and_b32_e32 v93, 0xffff0000, v91
	v_pk_fma_f32 v[86:87], v[94:95], v[92:93], v[86:87]
	v_lshlrev_b32_e32 v94, 16, v88
	v_pk_fma_f32 v[86:87], v[124:125], v[114:115], v[86:87]
	v_and_b32_e32 v95, 0xffff0000, v88
	v_mul_f32_e32 v91, 0xbfb8aa3b, v86
	v_exp_f32_e32 v91, v91
	v_pk_mul_f32 v[94:95], v[118:119], v[94:95]
	v_cndmask_b32_e32 v134, 0, v84, vcc
	v_cndmask_b32_e32 v135, 0, v85, vcc
	v_add_f32_e32 v91, 1.0, v91
	v_rcp_f32_e32 v92, v91
	v_mul_f32_e32 v91, 0xbfb8aa3b, v87
	v_exp_f32_e32 v91, v91
	v_lshlrev_b32_e32 v124, 16, v74
	v_and_b32_e32 v125, 0xffff0000, v74
	v_lshlrev_b32_e32 v122, 16, v123
	v_add_f32_e32 v91, 1.0, v91
	v_rcp_f32_e32 v93, v91
	v_cndmask_b32_e64 v91, 0, v78, s[4:5]
	v_and_b32_e32 v123, 0xffff0000, v123
	v_lshlrev_b64 v[106:107], 10, v[106:107]
	v_pk_mul_f32 v[114:115], v[86:87], v[92:93]
	v_lshlrev_b32_e32 v86, 16, v141
	v_and_b32_e32 v87, 0xffff0000, v141
	v_lshlrev_b32_e32 v92, 16, v144
	v_and_b32_e32 v93, 0xffff0000, v144
	v_pk_fma_f32 v[86:87], v[110:111], v[86:87], v[94:95]
	v_lshl_add_u64 v[106:107], s[88:89], 0, v[106:107]
	s_waitcnt lgkmcnt(0)
	v_pk_fma_f32 v[86:87], v[126:127], v[92:93], v[86:87]
	v_cndmask_b32_e64 v126, 0, v79, s[4:5]
	v_mul_f32_e32 v88, 0xbfb8aa3b, v86
	v_exp_f32_e32 v88, v88
	v_cndmask_b32_e64 v127, 0, v80, s[4:5]
	v_lshl_add_u64 v[106:107], v[106:107], 0, s[40:41]
	v_and_b32_e32 v108, 15, v188
	v_add_f32_e32 v88, 1.0, v88
	v_rcp_f32_e32 v92, v88
	v_mul_f32_e32 v88, 0xbfb8aa3b, v87
	v_exp_f32_e32 v88, v88
	s_mov_b32 s26, s24
	s_mov_b32 s27, s24
	v_add_f32_e32 v88, 1.0, v88
	v_rcp_f32_e32 v93, v88
	v_lshlrev_b32_e32 v88, 16, v89
	v_and_b32_e32 v89, 0xffff0000, v89
	v_pk_mul_f32 v[88:89], v[120:121], v[88:89]
	v_pk_mul_f32 v[110:111], v[86:87], v[92:93]
	v_lshlrev_b32_e32 v86, 16, v142
	v_and_b32_e32 v87, 0xffff0000, v142
	v_lshlrev_b32_e32 v92, 16, v145
	v_and_b32_e32 v93, 0xffff0000, v145
	v_pk_fma_f32 v[86:87], v[112:113], v[86:87], v[88:89]
	v_cvt_pk_bf16_f32 v94, v110, v111
	v_pk_fma_f32 v[86:87], v[128:129], v[92:93], v[86:87]
	v_cvt_pk_bf16_f32 v92, v96, v97
	v_mul_f32_e32 v88, 0xbfb8aa3b, v86
	v_mul_f32_e32 v89, 0xbfb8aa3b, v87
	v_exp_f32_e32 v88, v88
	v_exp_f32_e32 v89, v89
	v_cvt_pk_bf16_f32 v93, v114, v115
	v_cndmask_b32_e64 v128, 0, v81, s[4:5]
	v_add_f32_e32 v88, 1.0, v88
	v_add_f32_e32 v89, 1.0, v89
	v_rcp_f32_e32 v88, v88
	v_rcp_f32_e32 v89, v89
	v_cndmask_b32_e32 v129, 0, v83, vcc
	v_pk_mul_f32 v[112:113], v[86:87], v[88:89]
	v_cndmask_b32_e64 v86, v139, v140, s[6:7]
	v_add_u32_e32 v86, v86, v138
	v_cndmask_b32_e64 v88, v214, v212, s[6:7]
	v_mov_b32_e32 v89, v1
	v_ashrrev_i32_e32 v87, 31, v86
	v_lshl_add_u64 v[88:89], s[78:79], 0, v[88:89]
	v_lshlrev_b64 v[86:87], 10, v[86:87]
	v_lshl_add_u64 v[86:87], v[88:89], 0, v[86:87]
	v_lshl_add_u64 v[86:87], v[86:87], 0, s[40:41]
	v_cvt_pk_bf16_f32 v95, v112, v113
	v_lshl_add_u64 v[86:87], v[86:87], 0, v[0:1]
	v_pk_mul_f32 v[88:89], v[104:105], v[96:97] op_sel_hi:[0,1]
	global_store_dwordx4 v[86:87], v[92:95], off
	v_readlane_b32 s6, v255, 21
	s_nop 0
	v_cvt_pk_bf16_f32 v92, v88, v89
	v_pk_mul_f32 v[88:89], v[104:105], v[114:115] op_sel_hi:[0,1]
	v_cvt_pk_bf16_f32 v93, v88, v89
	v_pk_mul_f32 v[88:89], v[104:105], v[110:111] op_sel_hi:[0,1]
	v_cvt_pk_bf16_f32 v94, v88, v89
	v_pk_mul_f32 v[88:89], v[104:105], v[112:113] op_sel_hi:[0,1]
	v_cvt_pk_bf16_f32 v95, v88, v89
	v_add3_u32 v88, 0, v109, v0
	ds_write_b128 v88, v[92:95]
	v_pk_mul_f32 v[92:93], v[100:101], v[96:97] op_sel_hi:[0,1]
	v_pk_mul_f32 v[94:95], v[100:101], v[114:115] op_sel_hi:[0,1]
	v_cvt_pk_bf16_f32 v92, v92, v93
	v_cvt_pk_bf16_f32 v93, v94, v95
	v_pk_mul_f32 v[94:95], v[100:101], v[110:111] op_sel_hi:[0,1]
	v_pk_mul_f32 v[96:97], v[100:101], v[112:113] op_sel_hi:[0,1]
	v_cvt_pk_bf16_f32 v94, v94, v95
	v_cvt_pk_bf16_f32 v95, v96, v97
	v_add3_u32 v89, s34, v109, v0
	ds_write_b128 v89, v[92:95]
	v_add_u32_e32 v96, s6, v90
	ds_read_b128 v[78:81], v96
	ds_read_b128 v[82:85], v96 offset:16
	ds_read_b128 v[92:95], v96 offset:1536
	ds_read_b128 v[110:113], v96 offset:1552
	ds_read_b128 v[114:117], v96 offset:3072
	ds_read_b128 v[118:121], v96 offset:3088
	v_lshlrev_b32_e32 v96, 16, v91
	v_and_b32_e32 v97, 0xffff0000, v91
	s_waitcnt lgkmcnt(3)
	v_pk_mul_f32 v[92:93], v[92:93], v[124:125]
	v_cndmask_b32_e64 v91, 0, v68, s[4:5]
	v_pk_fma_f32 v[78:79], v[78:79], v[96:97], v[92:93]
	v_lshlrev_b32_e32 v96, 16, v129
	s_waitcnt lgkmcnt(1)
	v_pk_fma_f32 v[78:79], v[114:115], v[122:123], v[78:79]
	v_and_b32_e32 v97, 0xffff0000, v129
	v_mul_f32_e32 v74, 0xbfb8aa3b, v78
	v_exp_f32_e32 v74, v74
	v_lshlrev_b32_e32 v114, 16, v62
	v_and_b32_e32 v115, 0xffff0000, v62
	v_lshlrev_b32_e32 v62, 16, v63
	v_add_f32_e32 v74, 1.0, v74
	v_rcp_f32_e32 v92, v74
	v_mul_f32_e32 v74, 0xbfb8aa3b, v79
	v_exp_f32_e32 v74, v74
	v_and_b32_e32 v63, 0xffff0000, v63
	v_add_f32_e32 v74, 1.0, v74
	v_rcp_f32_e32 v93, v74
	v_lshlrev_b32_e32 v74, 16, v75
	v_and_b32_e32 v75, 0xffff0000, v75
	v_pk_mul_f32 v[74:75], v[94:95], v[74:75]
	v_pk_mul_f32 v[78:79], v[78:79], v[92:93]
	v_lshlrev_b32_e32 v92, 16, v126
	v_and_b32_e32 v93, 0xffff0000, v126
	v_pk_fma_f32 v[74:75], v[80:81], v[92:93], v[74:75]
	v_lshlrev_b32_e32 v94, 16, v76
	v_pk_fma_f32 v[74:75], v[116:117], v[96:97], v[74:75]
	v_and_b32_e32 v95, 0xffff0000, v76
	v_mul_f32_e32 v80, 0xbfb8aa3b, v74
	v_mul_f32_e32 v81, 0xbfb8aa3b, v75
	v_exp_f32_e32 v80, v80
	v_exp_f32_e32 v81, v81
	v_pk_mul_f32 v[94:95], v[110:111], v[94:95]
	v_lshlrev_b32_e32 v92, 16, v134
	v_add_f32_e32 v80, 1.0, v80
	v_add_f32_e32 v81, 1.0, v81
	v_rcp_f32_e32 v80, v80
	v_rcp_f32_e32 v81, v81
	v_and_b32_e32 v93, 0xffff0000, v134
	v_cvt_pk_bf16_f32 v78, v78, v79
	v_cndmask_b32_e32 v116, 0, v71, vcc
	v_pk_mul_f32 v[74:75], v[74:75], v[80:81]
	v_lshlrev_b32_e32 v80, 16, v127
	v_and_b32_e32 v81, 0xffff0000, v127
	v_pk_fma_f32 v[80:81], v[82:83], v[80:81], v[94:95]
	v_cvt_pk_bf16_f32 v79, v74, v75
	s_waitcnt lgkmcnt(0)
	v_pk_fma_f32 v[80:81], v[118:119], v[92:93], v[80:81]
	v_lshlrev_b32_e32 v92, 16, v135
	v_mul_f32_e32 v76, 0xbfb8aa3b, v80
	v_exp_f32_e32 v76, v76
	v_and_b32_e32 v93, 0xffff0000, v135
	v_lshl_add_u64 v[74:75], v[106:107], 0, v[0:1]
	v_or_b32_e32 v119, 32, v90
	v_add_f32_e32 v76, 1.0, v76
	v_rcp_f32_e32 v82, v76
	v_mul_f32_e32 v76, 0xbfb8aa3b, v81
	v_exp_f32_e32 v76, v76
	v_add_u32_e32 v96, s8, v119
	v_cndmask_b32_e32 v107, 0, v70, vcc
	v_cndmask_b32_e32 v117, 0, v72, vcc
	v_add_f32_e32 v76, 1.0, v76
	v_rcp_f32_e32 v83, v76
	v_lshlrev_b32_e32 v76, 16, v77
	v_and_b32_e32 v77, 0xffff0000, v77
	v_pk_mul_f32 v[76:77], v[112:113], v[76:77]
	v_pk_mul_f32 v[80:81], v[80:81], v[82:83]
	v_lshlrev_b32_e32 v82, 16, v128
	v_and_b32_e32 v83, 0xffff0000, v128
	v_pk_fma_f32 v[76:77], v[84:85], v[82:83], v[76:77]
	v_cvt_pk_bf16_f32 v80, v80, v81
	v_pk_fma_f32 v[76:77], v[120:121], v[92:93], v[76:77]
	v_cndmask_b32_e32 v118, 0, v73, vcc
	v_mul_f32_e32 v82, 0xbfb8aa3b, v76
	v_mul_f32_e32 v83, 0xbfb8aa3b, v77
	v_exp_f32_e32 v82, v82
	v_exp_f32_e32 v83, v83
	v_lshlrev_b32_e32 v106, 16, v107
	v_and_b32_e32 v107, 0xffff0000, v107
	v_add_f32_e32 v82, 1.0, v82
	v_add_f32_e32 v83, 1.0, v83
	v_rcp_f32_e32 v82, v82
	v_rcp_f32_e32 v83, v83
	s_nop 0
	v_pk_mul_f32 v[76:77], v[76:77], v[82:83]
	s_nop 0
	v_cvt_pk_bf16_f32 v81, v76, v77
	v_add3_u32 v76, s35, v109, v0
	ds_write_b128 v76, v[78:81]
	global_store_dwordx4 v[74:75], v[78:81], off
	v_cndmask_b32_e64 v0, 0, v66, s[4:5]
	v_cndmask_b32_e64 v77, 0, v67, s[4:5]
	v_cndmask_b32_e64 v109, 0, v69, s[4:5]
	ds_read_b128 v[66:69], v96
	ds_read_b128 v[70:73], v96 offset:16
	ds_read_b128 v[78:81], v96 offset:1536
	ds_read_b128 v[82:85], v96 offset:1552
	ds_read_b128 v[92:95], v96 offset:3072
	ds_read_b128 v[110:113], v96 offset:3088
	v_lshlrev_b32_e32 v96, 16, v0
	v_and_b32_e32 v97, 0xffff0000, v0
	s_waitcnt lgkmcnt(3)
	v_pk_mul_f32 v[78:79], v[78:79], v[114:115]
	v_pk_mul_f32 v[62:63], v[80:81], v[62:63]
	v_pk_fma_f32 v[66:67], v[66:67], v[96:97], v[78:79]
	v_lshlrev_b32_e32 v80, 16, v64
	s_waitcnt lgkmcnt(1)
	v_pk_fma_f32 v[66:67], v[92:93], v[106:107], v[66:67]
	v_lshlrev_b32_e32 v92, 16, v116
	v_mul_f32_e32 v0, 0xbfb8aa3b, v66
	v_exp_f32_e32 v0, v0
	v_and_b32_e32 v93, 0xffff0000, v116
	v_and_b32_e32 v81, 0xffff0000, v64
	v_pk_mul_f32 v[80:81], v[82:83], v[80:81]
	v_add_f32_e32 v0, 1.0, v0
	v_rcp_f32_e32 v78, v0
	v_mul_f32_e32 v0, 0xbfb8aa3b, v67
	v_exp_f32_e32 v0, v0
	v_lshlrev_b32_e32 v64, 16, v65
	v_and_b32_e32 v65, 0xffff0000, v65
	v_pk_mul_f32 v[64:65], v[84:85], v[64:65]
	v_add_f32_e32 v0, 1.0, v0
	v_rcp_f32_e32 v79, v0
	v_cndmask_b32_e32 v85, 0, v58, vcc
	v_cndmask_b32_e32 v96, 0, v60, vcc
	v_cndmask_b32_e32 v97, 0, v61, vcc
	v_pk_mul_f32 v[66:67], v[66:67], v[78:79]
	v_lshlrev_b32_e32 v78, 16, v77
	v_and_b32_e32 v79, 0xffff0000, v77
	v_pk_fma_f32 v[62:63], v[68:69], v[78:79], v[62:63]
	v_lshlrev_b32_e32 v78, 16, v117
	v_pk_fma_f32 v[62:63], v[94:95], v[92:93], v[62:63]
	v_and_b32_e32 v79, 0xffff0000, v117
	v_mul_f32_e32 v0, 0xbfb8aa3b, v62
	v_exp_f32_e32 v0, v0
	v_cndmask_b32_e64 v77, 0, v55, s[4:5]
	v_cndmask_b32_e64 v94, 0, v57, s[4:5]
	v_cndmask_b32_e32 v95, 0, v59, vcc
	v_add_f32_e32 v0, 1.0, v0
	v_rcp_f32_e32 v68, v0
	v_mul_f32_e32 v0, 0xbfb8aa3b, v63
	v_exp_f32_e32 v0, v0
	v_lshlrev_b32_e32 v92, 16, v50
	v_and_b32_e32 v93, 0xffff0000, v50
	v_lshlrev_b32_e32 v84, 16, v85
	v_add_f32_e32 v0, 1.0, v0
	v_rcp_f32_e32 v69, v0
	v_and_b32_e32 v85, 0xffff0000, v85
	v_lshlrev_b32_e32 v50, 16, v51
	v_and_b32_e32 v51, 0xffff0000, v51
	v_pk_mul_f32 v[68:69], v[62:63], v[68:69]
	v_lshlrev_b32_e32 v62, 16, v91
	v_and_b32_e32 v63, 0xffff0000, v91
	v_pk_fma_f32 v[62:63], v[70:71], v[62:63], v[80:81]
	v_cndmask_b32_e64 v91, 0, v56, s[4:5]
	s_waitcnt lgkmcnt(0)
	v_pk_fma_f32 v[62:63], v[110:111], v[78:79], v[62:63]
	v_lshlrev_b32_e32 v78, 16, v118
	v_mul_f32_e32 v0, 0xbfb8aa3b, v62
	v_exp_f32_e32 v0, v0
	v_and_b32_e32 v79, 0xffff0000, v118
	v_add_f32_e32 v0, 1.0, v0
	v_rcp_f32_e32 v70, v0
	v_mul_f32_e32 v0, 0xbfb8aa3b, v63
	v_exp_f32_e32 v0, v0
	s_nop 0
	v_add_f32_e32 v0, 1.0, v0
	v_rcp_f32_e32 v71, v0
	s_nop 0
	v_pk_mul_f32 v[70:71], v[62:63], v[70:71]
	v_lshlrev_b32_e32 v62, 16, v109
	v_and_b32_e32 v63, 0xffff0000, v109
	v_pk_fma_f32 v[62:63], v[72:73], v[62:63], v[64:65]
	s_nop 0
	v_pk_fma_f32 v[62:63], v[112:113], v[78:79], v[62:63]
	s_nop 0
	v_mul_f32_e32 v0, 0xbfb8aa3b, v62
	v_exp_f32_e32 v0, v0
	s_nop 0
	v_add_f32_e32 v0, 1.0, v0
	v_rcp_f32_e32 v64, v0
	v_mul_f32_e32 v0, 0xbfb8aa3b, v63
	v_exp_f32_e32 v0, v0
	s_nop 0
	v_add_f32_e32 v0, 1.0, v0
	v_rcp_f32_e32 v65, v0
	v_cndmask_b32_e64 v0, 0, v54, s[4:5]
	v_lshlrev_b32_e32 v82, 16, v0
	v_and_b32_e32 v83, 0xffff0000, v0
	v_pk_mul_f32 v[72:73], v[62:63], v[64:65]
	v_cvt_pk_bf16_f32 v62, v66, v67
	v_cvt_pk_bf16_f32 v63, v68, v69
	v_cvt_pk_bf16_f32 v64, v70, v71
	v_cvt_pk_bf16_f32 v65, v72, v73
	global_store_dwordx4 v[86:87], v[62:65], off offset:16
	v_pk_mul_f32 v[78:79], v[104:105], v[72:73] op_sel_hi:[0,1]
	s_nop 0
	v_pk_mul_f32 v[62:63], v[104:105], v[66:67] op_sel_hi:[0,1]
	v_pk_mul_f32 v[64:65], v[104:105], v[68:69] op_sel_hi:[0,1]
	v_cvt_pk_bf16_f32 v62, v62, v63
	v_cvt_pk_bf16_f32 v63, v64, v65
	v_pk_mul_f32 v[64:65], v[104:105], v[70:71] op_sel_hi:[0,1]
	v_cvt_pk_bf16_f32 v64, v64, v65
	v_cvt_pk_bf16_f32 v65, v78, v79
	ds_write_b128 v88, v[62:65] offset:16
	v_pk_mul_f32 v[62:63], v[100:101], v[66:67] op_sel_hi:[0,1]
	v_pk_mul_f32 v[64:65], v[100:101], v[68:69] op_sel_hi:[0,1]
	v_cvt_pk_bf16_f32 v62, v62, v63
	v_cvt_pk_bf16_f32 v63, v64, v65
	v_pk_mul_f32 v[64:65], v[100:101], v[70:71] op_sel_hi:[0,1]
	v_pk_mul_f32 v[66:67], v[100:101], v[72:73] op_sel_hi:[0,1]
	v_cvt_pk_bf16_f32 v64, v64, v65
	v_cvt_pk_bf16_f32 v65, v66, v67
	ds_write_b128 v89, v[62:65] offset:16
	v_add_u32_e32 v78, s6, v119
	ds_read_b128 v[54:57], v78
	ds_read_b128 v[58:61], v78 offset:16
	ds_read_b128 v[62:65], v78 offset:1536
	ds_read_b128 v[66:69], v78 offset:1552
	ds_read_b128 v[70:73], v78 offset:3072
	ds_read_b128 v[78:81], v78 offset:3088
	s_waitcnt lgkmcnt(3)
	v_pk_mul_f32 v[62:63], v[62:63], v[92:93]
	s_nop 0
	v_pk_fma_f32 v[54:55], v[54:55], v[82:83], v[62:63]
	v_pk_mul_f32 v[50:51], v[64:65], v[50:51]
	s_waitcnt lgkmcnt(1)
	v_pk_fma_f32 v[54:55], v[70:71], v[84:85], v[54:55]
	v_lshlrev_b32_e32 v70, 16, v95
	v_mul_f32_e32 v0, 0xbfb8aa3b, v54
	v_exp_f32_e32 v0, v0
	v_and_b32_e32 v71, 0xffff0000, v95
	v_lshlrev_b32_e32 v64, 16, v52
	v_and_b32_e32 v65, 0xffff0000, v52
	v_add_f32_e32 v0, 1.0, v0
	v_rcp_f32_e32 v62, v0
	v_mul_f32_e32 v0, 0xbfb8aa3b, v55
	v_exp_f32_e32 v0, v0
	v_pk_mul_f32 v[64:65], v[66:67], v[64:65]
	v_lshlrev_b32_e32 v52, 16, v53
	v_and_b32_e32 v53, 0xffff0000, v53
	v_add_f32_e32 v0, 1.0, v0
	v_rcp_f32_e32 v63, v0
	v_pk_mul_f32 v[52:53], v[68:69], v[52:53]
	v_cndmask_b32_e32 v69, 0, v46, vcc
	v_lshlrev_b32_e32 v68, 16, v69
	v_pk_mul_f32 v[54:55], v[54:55], v[62:63]
	v_lshlrev_b32_e32 v62, 16, v77
	v_and_b32_e32 v63, 0xffff0000, v77
	v_pk_fma_f32 v[50:51], v[56:57], v[62:63], v[50:51]
	v_lshlrev_b32_e32 v62, 16, v96
	v_pk_fma_f32 v[50:51], v[72:73], v[70:71], v[50:51]
	v_and_b32_e32 v63, 0xffff0000, v96
	v_mul_f32_e32 v0, 0xbfb8aa3b, v50
	v_exp_f32_e32 v0, v0
	v_cndmask_b32_e64 v72, 0, v43, s[4:5]
	v_cndmask_b32_e64 v73, 0, v44, s[4:5]
	v_cndmask_b32_e64 v77, 0, v45, s[4:5]
	v_add_f32_e32 v0, 1.0, v0
	v_rcp_f32_e32 v56, v0
	v_mul_f32_e32 v0, 0xbfb8aa3b, v51
	v_exp_f32_e32 v0, v0
	v_lshlrev_b32_e32 v70, 16, v38
	v_and_b32_e32 v71, 0xffff0000, v38
	v_and_b32_e32 v69, 0xffff0000, v69
	v_add_f32_e32 v0, 1.0, v0
	v_rcp_f32_e32 v57, v0
	v_lshlrev_b32_e32 v38, 16, v39
	v_and_b32_e32 v39, 0xffff0000, v39
	v_pk_mul_f32 v[56:57], v[50:51], v[56:57]
	v_lshlrev_b32_e32 v50, 16, v91
	v_and_b32_e32 v51, 0xffff0000, v91
	v_pk_fma_f32 v[50:51], v[58:59], v[50:51], v[64:65]
	s_waitcnt lgkmcnt(0)
	v_pk_fma_f32 v[50:51], v[78:79], v[62:63], v[50:51]
	v_lshlrev_b32_e32 v62, 16, v97
	v_mul_f32_e32 v0, 0xbfb8aa3b, v50
	v_exp_f32_e32 v0, v0
	v_and_b32_e32 v63, 0xffff0000, v97
	v_cndmask_b32_e32 v78, 0, v47, vcc
	v_cndmask_b32_e32 v79, 0, v48, vcc
	v_add_f32_e32 v0, 1.0, v0
	v_rcp_f32_e32 v58, v0
	v_mul_f32_e32 v0, 0xbfb8aa3b, v51
	v_exp_f32_e32 v0, v0
	s_nop 0
	v_add_f32_e32 v0, 1.0, v0
	v_rcp_f32_e32 v59, v0
	s_nop 0
	v_pk_mul_f32 v[58:59], v[50:51], v[58:59]
	v_lshlrev_b32_e32 v50, 16, v94
	v_and_b32_e32 v51, 0xffff0000, v94
	v_pk_fma_f32 v[50:51], v[60:61], v[50:51], v[52:53]
	s_nop 0
	v_pk_fma_f32 v[50:51], v[80:81], v[62:63], v[50:51]
	v_or_b32_e32 v81, 64, v90
	v_mul_f32_e32 v0, 0xbfb8aa3b, v50
	v_exp_f32_e32 v0, v0
	v_add_u32_e32 v62, s8, v81
	v_cndmask_b32_e32 v80, 0, v49, vcc
	v_add_f32_e32 v0, 1.0, v0
	v_rcp_f32_e32 v52, v0
	v_mul_f32_e32 v0, 0xbfb8aa3b, v51
	v_exp_f32_e32 v0, v0
	s_nop 0
	v_add_f32_e32 v0, 1.0, v0
	v_rcp_f32_e32 v53, v0
	v_cndmask_b32_e64 v0, 0, v42, s[4:5]
	v_lshlrev_b32_e32 v66, 16, v0
	v_and_b32_e32 v67, 0xffff0000, v0
	v_pk_mul_f32 v[60:61], v[50:51], v[52:53]
	v_cvt_pk_bf16_f32 v50, v54, v55
	v_cvt_pk_bf16_f32 v51, v56, v57
	v_cvt_pk_bf16_f32 v52, v58, v59
	v_cvt_pk_bf16_f32 v53, v60, v61
	ds_write_b128 v76, v[50:53] offset:16
	global_store_dwordx4 v[74:75], v[50:53], off offset:16
	ds_read_b128 v[42:45], v62
	ds_read_b128 v[46:49], v62 offset:16
	ds_read_b128 v[50:53], v62 offset:1536
	ds_read_b128 v[54:57], v62 offset:1552
	ds_read_b128 v[58:61], v62 offset:3072
	ds_read_b128 v[62:65], v62 offset:3088
	s_waitcnt lgkmcnt(3)
	v_pk_mul_f32 v[50:51], v[50:51], v[70:71]
	s_nop 0
	v_pk_fma_f32 v[42:43], v[42:43], v[66:67], v[50:51]
	v_pk_mul_f32 v[38:39], v[52:53], v[38:39]
	s_waitcnt lgkmcnt(1)
	v_pk_fma_f32 v[42:43], v[58:59], v[68:69], v[42:43]
	v_lshlrev_b32_e32 v58, 16, v78
	v_mul_f32_e32 v0, 0xbfb8aa3b, v42
	v_exp_f32_e32 v0, v0
	v_and_b32_e32 v59, 0xffff0000, v78
	v_lshlrev_b32_e32 v52, 16, v40
	v_and_b32_e32 v53, 0xffff0000, v40
	v_add_f32_e32 v0, 1.0, v0
	v_rcp_f32_e32 v50, v0
	v_mul_f32_e32 v0, 0xbfb8aa3b, v43
	v_exp_f32_e32 v0, v0
	v_pk_mul_f32 v[52:53], v[54:55], v[52:53]
	v_lshlrev_b32_e32 v40, 16, v41
	v_and_b32_e32 v41, 0xffff0000, v41
	v_add_f32_e32 v0, 1.0, v0
	v_rcp_f32_e32 v51, v0
	v_pk_mul_f32 v[40:41], v[56:57], v[40:41]
	v_cndmask_b32_e32 v57, 0, v34, vcc
	v_lshlrev_b32_e32 v56, 16, v57
	v_pk_mul_f32 v[42:43], v[42:43], v[50:51]
	v_lshlrev_b32_e32 v50, 16, v72
	v_and_b32_e32 v51, 0xffff0000, v72
	v_pk_fma_f32 v[38:39], v[44:45], v[50:51], v[38:39]
	v_lshlrev_b32_e32 v50, 16, v79
	v_pk_fma_f32 v[38:39], v[60:61], v[58:59], v[38:39]
	v_and_b32_e32 v51, 0xffff0000, v79
	v_mul_f32_e32 v0, 0xbfb8aa3b, v38
	v_exp_f32_e32 v0, v0
	v_cndmask_b32_e64 v60, 0, v31, s[4:5]
	v_cndmask_b32_e64 v61, 0, v32, s[4:5]
	v_lshlrev_b32_e32 v58, 16, v26
	v_add_f32_e32 v0, 1.0, v0
	v_rcp_f32_e32 v44, v0
	v_mul_f32_e32 v0, 0xbfb8aa3b, v39
	v_exp_f32_e32 v0, v0
	v_and_b32_e32 v59, 0xffff0000, v26
	v_and_b32_e32 v57, 0xffff0000, v57
	v_lshlrev_b32_e32 v26, 16, v27
	v_add_f32_e32 v0, 1.0, v0
	v_rcp_f32_e32 v45, v0
	v_and_b32_e32 v27, 0xffff0000, v27
	v_pk_mul_f32 v[44:45], v[38:39], v[44:45]
	v_lshlrev_b32_e32 v38, 16, v73
	v_and_b32_e32 v39, 0xffff0000, v73
	v_pk_fma_f32 v[38:39], v[46:47], v[38:39], v[52:53]
	s_waitcnt lgkmcnt(0)
	v_pk_fma_f32 v[38:39], v[62:63], v[50:51], v[38:39]
	v_lshlrev_b32_e32 v50, 16, v80
	v_mul_f32_e32 v0, 0xbfb8aa3b, v38
	v_exp_f32_e32 v0, v0
	v_and_b32_e32 v51, 0xffff0000, v80
	v_cndmask_b32_e64 v62, 0, v33, s[4:5]
	v_cndmask_b32_e32 v63, 0, v35, vcc
	v_add_f32_e32 v0, 1.0, v0
	v_rcp_f32_e32 v46, v0
	v_mul_f32_e32 v0, 0xbfb8aa3b, v39
	v_exp_f32_e32 v0, v0
	s_nop 0
	v_add_f32_e32 v0, 1.0, v0
	v_rcp_f32_e32 v47, v0
	s_nop 0
	v_pk_mul_f32 v[46:47], v[38:39], v[46:47]
	v_lshlrev_b32_e32 v38, 16, v77
	v_and_b32_e32 v39, 0xffff0000, v77
	v_pk_fma_f32 v[38:39], v[48:49], v[38:39], v[40:41]
	s_nop 0
	v_pk_fma_f32 v[38:39], v[64:65], v[50:51], v[38:39]
	v_cndmask_b32_e32 v64, 0, v36, vcc
	v_mul_f32_e32 v0, 0xbfb8aa3b, v38
	v_exp_f32_e32 v0, v0
	v_cndmask_b32_e32 v65, 0, v37, vcc
	v_add_f32_e32 v0, 1.0, v0
	v_rcp_f32_e32 v40, v0
	v_mul_f32_e32 v0, 0xbfb8aa3b, v39
	v_exp_f32_e32 v0, v0
	s_nop 0
	v_add_f32_e32 v0, 1.0, v0
	v_rcp_f32_e32 v41, v0
	v_cndmask_b32_e64 v0, 0, v30, s[4:5]
	v_lshlrev_b32_e32 v54, 16, v0
	v_and_b32_e32 v55, 0xffff0000, v0
	v_pk_mul_f32 v[48:49], v[38:39], v[40:41]
	v_cvt_pk_bf16_f32 v38, v42, v43
	v_cvt_pk_bf16_f32 v39, v44, v45
	v_cvt_pk_bf16_f32 v40, v46, v47
	v_cvt_pk_bf16_f32 v41, v48, v49
	global_store_dwordx4 v[86:87], v[38:41], off offset:32
	v_pk_mul_f32 v[50:51], v[104:105], v[48:49] op_sel_hi:[0,1]
	s_nop 0
	v_pk_mul_f32 v[38:39], v[104:105], v[42:43] op_sel_hi:[0,1]
	v_pk_mul_f32 v[40:41], v[104:105], v[44:45] op_sel_hi:[0,1]
	v_cvt_pk_bf16_f32 v38, v38, v39
	v_cvt_pk_bf16_f32 v39, v40, v41
	v_pk_mul_f32 v[40:41], v[104:105], v[46:47] op_sel_hi:[0,1]
	v_cvt_pk_bf16_f32 v40, v40, v41
	v_cvt_pk_bf16_f32 v41, v50, v51
	ds_write_b128 v88, v[38:41] offset:32
	v_pk_mul_f32 v[38:39], v[100:101], v[42:43] op_sel_hi:[0,1]
	v_pk_mul_f32 v[40:41], v[100:101], v[44:45] op_sel_hi:[0,1]
	v_cvt_pk_bf16_f32 v38, v38, v39
	v_cvt_pk_bf16_f32 v39, v40, v41
	v_pk_mul_f32 v[40:41], v[100:101], v[46:47] op_sel_hi:[0,1]
	v_pk_mul_f32 v[42:43], v[100:101], v[48:49] op_sel_hi:[0,1]
	v_cvt_pk_bf16_f32 v40, v40, v41
	v_cvt_pk_bf16_f32 v41, v42, v43
	ds_write_b128 v89, v[38:41] offset:32
	v_add_u32_e32 v50, s6, v81
	ds_read_b128 v[30:33], v50
	ds_read_b128 v[34:37], v50 offset:16
	ds_read_b128 v[38:41], v50 offset:1536
	ds_read_b128 v[42:45], v50 offset:1552
	ds_read_b128 v[46:49], v50 offset:3072
	ds_read_b128 v[50:53], v50 offset:3088
	s_waitcnt lgkmcnt(3)
	v_pk_mul_f32 v[38:39], v[38:39], v[58:59]
	s_nop 0
	v_pk_fma_f32 v[30:31], v[30:31], v[54:55], v[38:39]
	v_pk_mul_f32 v[26:27], v[40:41], v[26:27]
	s_waitcnt lgkmcnt(1)
	v_pk_fma_f32 v[30:31], v[46:47], v[56:57], v[30:31]
	v_lshlrev_b32_e32 v46, 16, v63
	v_mul_f32_e32 v0, 0xbfb8aa3b, v30
	v_exp_f32_e32 v0, v0
	v_and_b32_e32 v47, 0xffff0000, v63
	v_lshlrev_b32_e32 v40, 16, v28
	v_and_b32_e32 v41, 0xffff0000, v28
	v_add_f32_e32 v0, 1.0, v0
	v_rcp_f32_e32 v38, v0
	v_mul_f32_e32 v0, 0xbfb8aa3b, v31
	v_exp_f32_e32 v0, v0
	v_pk_mul_f32 v[40:41], v[42:43], v[40:41]
	v_lshlrev_b32_e32 v28, 16, v29
	v_and_b32_e32 v29, 0xffff0000, v29
	v_add_f32_e32 v0, 1.0, v0
	v_rcp_f32_e32 v39, v0
	v_pk_mul_f32 v[28:29], v[44:45], v[28:29]
	v_or_b32_e32 v54, 0x60, v90
	v_cndmask_b32_e32 v45, 0, v22, vcc
	v_pk_mul_f32 v[30:31], v[30:31], v[38:39]
	v_lshlrev_b32_e32 v38, 16, v60
	v_and_b32_e32 v39, 0xffff0000, v60
	v_pk_fma_f32 v[26:27], v[32:33], v[38:39], v[26:27]
	v_lshlrev_b32_e32 v38, 16, v64
	v_pk_fma_f32 v[26:27], v[48:49], v[46:47], v[26:27]
	v_and_b32_e32 v39, 0xffff0000, v64
	v_mul_f32_e32 v0, 0xbfb8aa3b, v26
	v_exp_f32_e32 v0, v0
	v_cndmask_b32_e64 v48, 0, v19, s[4:5]
	v_cndmask_b32_e64 v49, 0, v20, s[4:5]
	v_lshlrev_b32_e32 v46, 16, v14
	v_add_f32_e32 v0, 1.0, v0
	v_rcp_f32_e32 v32, v0
	v_mul_f32_e32 v0, 0xbfb8aa3b, v27
	v_exp_f32_e32 v0, v0
	v_and_b32_e32 v47, 0xffff0000, v14
	v_lshlrev_b32_e32 v44, 16, v45
	v_and_b32_e32 v45, 0xffff0000, v45
	v_add_f32_e32 v0, 1.0, v0
	v_rcp_f32_e32 v33, v0
	v_lshlrev_b32_e32 v14, 16, v15
	v_and_b32_e32 v15, 0xffff0000, v15
	v_pk_mul_f32 v[32:33], v[26:27], v[32:33]
	v_lshlrev_b32_e32 v26, 16, v61
	v_and_b32_e32 v27, 0xffff0000, v61
	v_pk_fma_f32 v[26:27], v[34:35], v[26:27], v[40:41]
	s_waitcnt lgkmcnt(0)
	v_pk_fma_f32 v[26:27], v[50:51], v[38:39], v[26:27]
	v_lshlrev_b32_e32 v38, 16, v65
	v_mul_f32_e32 v0, 0xbfb8aa3b, v26
	v_exp_f32_e32 v0, v0
	v_and_b32_e32 v39, 0xffff0000, v65
	v_cndmask_b32_e64 v50, 0, v21, s[4:5]
	v_cndmask_b32_e32 v51, 0, v23, vcc
	v_add_f32_e32 v0, 1.0, v0
	v_rcp_f32_e32 v34, v0
	v_mul_f32_e32 v0, 0xbfb8aa3b, v27
	v_exp_f32_e32 v0, v0
	s_nop 0
	v_add_f32_e32 v0, 1.0, v0
	v_rcp_f32_e32 v35, v0
	s_nop 0
	v_pk_mul_f32 v[34:35], v[26:27], v[34:35]
	v_lshlrev_b32_e32 v26, 16, v62
	v_and_b32_e32 v27, 0xffff0000, v62
	v_pk_fma_f32 v[26:27], v[36:37], v[26:27], v[28:29]
	s_nop 0
	v_pk_fma_f32 v[26:27], v[52:53], v[38:39], v[26:27]
	v_add_u32_e32 v38, s8, v54
	v_mul_f32_e32 v0, 0xbfb8aa3b, v26
	v_exp_f32_e32 v0, v0
	v_cndmask_b32_e32 v52, 0, v24, vcc
	v_cndmask_b32_e32 v53, 0, v25, vcc
	v_add_f32_e32 v0, 1.0, v0
	v_rcp_f32_e32 v28, v0
	v_mul_f32_e32 v0, 0xbfb8aa3b, v27
	v_exp_f32_e32 v0, v0
	s_nop 0
	v_add_f32_e32 v0, 1.0, v0
	v_rcp_f32_e32 v29, v0
	v_cndmask_b32_e64 v0, 0, v18, s[4:5]
	v_lshlrev_b32_e32 v42, 16, v0
	v_and_b32_e32 v43, 0xffff0000, v0
	v_pk_mul_f32 v[36:37], v[26:27], v[28:29]
	v_cvt_pk_bf16_f32 v26, v30, v31
	v_cvt_pk_bf16_f32 v27, v32, v33
	v_cvt_pk_bf16_f32 v28, v34, v35
	v_cvt_pk_bf16_f32 v29, v36, v37
	ds_write_b128 v76, v[26:29] offset:32
	global_store_dwordx4 v[74:75], v[26:29], off offset:32
	ds_read_b128 v[18:21], v38
	ds_read_b128 v[22:25], v38 offset:16
	ds_read_b128 v[26:29], v38 offset:1536
	ds_read_b128 v[30:33], v38 offset:1552
	ds_read_b128 v[34:37], v38 offset:3072
	ds_read_b128 v[38:41], v38 offset:3088
	s_waitcnt lgkmcnt(3)
	v_pk_mul_f32 v[26:27], v[26:27], v[46:47]
	s_nop 0
	v_pk_fma_f32 v[18:19], v[18:19], v[42:43], v[26:27]
	v_pk_mul_f32 v[14:15], v[28:29], v[14:15]
	s_waitcnt lgkmcnt(1)
	v_pk_fma_f32 v[18:19], v[34:35], v[44:45], v[18:19]
	v_lshlrev_b32_e32 v34, 16, v51
	v_mul_f32_e32 v0, 0xbfb8aa3b, v18
	v_exp_f32_e32 v0, v0
	v_and_b32_e32 v35, 0xffff0000, v51
	v_lshlrev_b32_e32 v28, 16, v16
	v_and_b32_e32 v29, 0xffff0000, v16
	v_add_f32_e32 v0, 1.0, v0
	v_rcp_f32_e32 v26, v0
	v_mul_f32_e32 v0, 0xbfb8aa3b, v19
	v_exp_f32_e32 v0, v0
	v_pk_mul_f32 v[28:29], v[30:31], v[28:29]
	v_lshlrev_b32_e32 v16, 16, v17
	v_and_b32_e32 v17, 0xffff0000, v17
	v_add_f32_e32 v0, 1.0, v0
	v_rcp_f32_e32 v27, v0
	v_pk_mul_f32 v[16:17], v[32:33], v[16:17]
	v_cndmask_b32_e32 v33, 0, v10, vcc
	v_lshlrev_b32_e32 v32, 16, v33
	v_pk_mul_f32 v[18:19], v[18:19], v[26:27]
	v_lshlrev_b32_e32 v26, 16, v48
	v_and_b32_e32 v27, 0xffff0000, v48
	v_pk_fma_f32 v[14:15], v[20:21], v[26:27], v[14:15]
	v_lshlrev_b32_e32 v26, 16, v52
	v_pk_fma_f32 v[14:15], v[36:37], v[34:35], v[14:15]
	v_and_b32_e32 v27, 0xffff0000, v52
	v_mul_f32_e32 v0, 0xbfb8aa3b, v14
	v_exp_f32_e32 v0, v0
	v_cndmask_b32_e64 v36, 0, v7, s[4:5]
	v_cndmask_b32_e64 v37, 0, v8, s[4:5]
	v_lshlrev_b32_e32 v34, 16, v2
	v_add_f32_e32 v0, 1.0, v0
	v_rcp_f32_e32 v20, v0
	v_mul_f32_e32 v0, 0xbfb8aa3b, v15
	v_exp_f32_e32 v0, v0
	v_and_b32_e32 v35, 0xffff0000, v2
	v_and_b32_e32 v33, 0xffff0000, v33
	v_lshlrev_b32_e32 v2, 16, v3
	v_add_f32_e32 v0, 1.0, v0
	v_rcp_f32_e32 v21, v0
	v_and_b32_e32 v3, 0xffff0000, v3
	v_pk_mul_f32 v[20:21], v[14:15], v[20:21]
	v_lshlrev_b32_e32 v14, 16, v49
	v_and_b32_e32 v15, 0xffff0000, v49
	v_pk_fma_f32 v[14:15], v[22:23], v[14:15], v[28:29]
	s_waitcnt lgkmcnt(0)
	v_pk_fma_f32 v[14:15], v[38:39], v[26:27], v[14:15]
	v_lshlrev_b32_e32 v26, 16, v53
	v_mul_f32_e32 v0, 0xbfb8aa3b, v14
	v_exp_f32_e32 v0, v0
	v_and_b32_e32 v27, 0xffff0000, v53
	v_cndmask_b32_e64 v38, 0, v9, s[4:5]
	v_cndmask_b32_e32 v39, 0, v11, vcc
	v_add_f32_e32 v0, 1.0, v0
	v_rcp_f32_e32 v22, v0
	v_mul_f32_e32 v0, 0xbfb8aa3b, v15
	v_exp_f32_e32 v0, v0
	s_nop 0
	v_add_f32_e32 v0, 1.0, v0
	v_rcp_f32_e32 v23, v0
	s_nop 0
	v_pk_mul_f32 v[22:23], v[14:15], v[22:23]
	v_lshlrev_b32_e32 v14, 16, v50
	v_and_b32_e32 v15, 0xffff0000, v50
	v_pk_fma_f32 v[14:15], v[24:25], v[14:15], v[16:17]
	s_nop 0
	v_pk_fma_f32 v[14:15], v[40:41], v[26:27], v[14:15]
	v_cndmask_b32_e32 v40, 0, v12, vcc
	v_mul_f32_e32 v0, 0xbfb8aa3b, v14
	v_exp_f32_e32 v0, v0
	v_cndmask_b32_e32 v41, 0, v13, vcc
	v_cmp_eq_u32_e32 vcc, 0, v108
	v_add_f32_e32 v0, 1.0, v0
	v_rcp_f32_e32 v16, v0
	v_mul_f32_e32 v0, 0xbfb8aa3b, v15
	v_exp_f32_e32 v0, v0
	s_nop 0
	v_add_f32_e32 v0, 1.0, v0
	v_rcp_f32_e32 v17, v0
	v_cndmask_b32_e64 v0, 0, v6, s[4:5]
	v_lshlrev_b32_e32 v30, 16, v0
	v_and_b32_e32 v31, 0xffff0000, v0
	v_pk_mul_f32 v[24:25], v[14:15], v[16:17]
	v_cvt_pk_bf16_f32 v14, v18, v19
	v_cvt_pk_bf16_f32 v15, v20, v21
	v_cvt_pk_bf16_f32 v16, v22, v23
	v_cvt_pk_bf16_f32 v17, v24, v25
	global_store_dwordx4 v[86:87], v[14:17], off offset:48
	v_pk_mul_f32 v[26:27], v[104:105], v[24:25] op_sel_hi:[0,1]
	s_lshl_b32 s4, s31, 3
	v_pk_mul_f32 v[14:15], v[104:105], v[18:19] op_sel_hi:[0,1]
	v_pk_mul_f32 v[16:17], v[104:105], v[20:21] op_sel_hi:[0,1]
	v_cvt_pk_bf16_f32 v14, v14, v15
	v_cvt_pk_bf16_f32 v15, v16, v17
	v_pk_mul_f32 v[16:17], v[104:105], v[22:23] op_sel_hi:[0,1]
	v_cvt_pk_bf16_f32 v16, v16, v17
	v_cvt_pk_bf16_f32 v17, v26, v27
	ds_write_b128 v88, v[14:17] offset:48
	v_pk_mul_f32 v[14:15], v[100:101], v[18:19] op_sel_hi:[0,1]
	v_pk_mul_f32 v[16:17], v[100:101], v[20:21] op_sel_hi:[0,1]
	v_cvt_pk_bf16_f32 v14, v14, v15
	v_cvt_pk_bf16_f32 v15, v16, v17
	v_pk_mul_f32 v[16:17], v[100:101], v[22:23] op_sel_hi:[0,1]
	v_pk_mul_f32 v[18:19], v[100:101], v[24:25] op_sel_hi:[0,1]
	v_cvt_pk_bf16_f32 v16, v16, v17
	v_cvt_pk_bf16_f32 v17, v18, v19
	ds_write_b128 v89, v[14:17] offset:48
	v_add_u32_e32 v26, s6, v54
	ds_read_b128 v[6:9], v26
	ds_read_b128 v[10:13], v26 offset:16
	ds_read_b128 v[14:17], v26 offset:1536
	ds_read_b128 v[18:21], v26 offset:1552
	ds_read_b128 v[22:25], v26 offset:3072
	ds_read_b128 v[26:29], v26 offset:3088
	s_or_b32 s10, s4, s25
	s_waitcnt lgkmcnt(3)
	v_pk_mul_f32 v[14:15], v[14:15], v[34:35]
	v_pk_mul_f32 v[2:3], v[16:17], v[2:3]
	v_pk_fma_f32 v[6:7], v[6:7], v[30:31], v[14:15]
	v_lshlrev_b32_e32 v16, 16, v4
	s_waitcnt lgkmcnt(1)
	v_pk_fma_f32 v[6:7], v[22:23], v[32:33], v[6:7]
	v_lshlrev_b32_e32 v22, 16, v39
	v_mul_f32_e32 v0, 0xbfb8aa3b, v6
	v_exp_f32_e32 v0, v0
	v_and_b32_e32 v23, 0xffff0000, v39
	v_and_b32_e32 v17, 0xffff0000, v4
	v_pk_mul_f32 v[16:17], v[18:19], v[16:17]
	v_add_f32_e32 v0, 1.0, v0
	v_rcp_f32_e32 v14, v0
	v_mul_f32_e32 v0, 0xbfb8aa3b, v7
	v_exp_f32_e32 v0, v0
	v_lshlrev_b32_e32 v4, 16, v5
	v_and_b32_e32 v5, 0xffff0000, v5
	v_pk_mul_f32 v[4:5], v[20:21], v[4:5]
	v_add_f32_e32 v0, 1.0, v0
	v_rcp_f32_e32 v15, v0
	v_lshlrev_b32_e32 v18, 4, v103
	v_or_b32_e32 v20, v18, v108
	v_ashrrev_i32_e32 v21, 31, v20
	v_pk_mul_f32 v[6:7], v[6:7], v[14:15]
	v_lshlrev_b32_e32 v14, 16, v36
	v_and_b32_e32 v15, 0xffff0000, v36
	v_pk_fma_f32 v[2:3], v[8:9], v[14:15], v[2:3]
	v_lshlrev_b32_e32 v14, 16, v40
	v_pk_fma_f32 v[2:3], v[24:25], v[22:23], v[2:3]
	v_and_b32_e32 v15, 0xffff0000, v40
	v_mul_f32_e32 v0, 0xbfb8aa3b, v2
	v_exp_f32_e32 v0, v0
	v_lshlrev_b64 v[20:21], 8, v[20:21]
	v_lshl_add_u64 v[20:21], s[90:91], 0, v[20:21]
	v_ashrrev_i32_e32 v19, 31, v18
	v_add_f32_e32 v0, 1.0, v0
	v_rcp_f32_e32 v8, v0
	v_mul_f32_e32 v0, 0xbfb8aa3b, v3
	v_exp_f32_e32 v0, v0
	v_lshl_add_u64 v[18:19], v[18:19], 2, s[52:53]
	s_mul_i32 s10, s10, 18
	s_add_i32 s6, s10, s30
	v_add_f32_e32 v0, 1.0, v0
	v_rcp_f32_e32 v9, v0
	s_ashr_i32 s7, s6, 31
	s_lshl_b64 s[4:5], s[6:7], 15
	s_mov_b32 s25, s24
	v_pk_mul_f32 v[8:9], v[2:3], v[8:9]
	v_lshlrev_b32_e32 v2, 16, v37
	v_and_b32_e32 v3, 0xffff0000, v37
	v_pk_fma_f32 v[2:3], v[10:11], v[2:3], v[16:17]
	s_waitcnt lgkmcnt(0)
	v_pk_fma_f32 v[2:3], v[26:27], v[14:15], v[2:3]
	v_lshlrev_b32_e32 v14, 16, v41
	v_mul_f32_e32 v0, 0xbfb8aa3b, v2
	v_exp_f32_e32 v0, v0
	v_and_b32_e32 v15, 0xffff0000, v41
	v_lshlrev_b32_e32 v26, 5, v103
	v_add_f32_e32 v0, 1.0, v0
	v_rcp_f32_e32 v10, v0
	v_mul_f32_e32 v0, 0xbfb8aa3b, v3
	v_exp_f32_e32 v0, v0
	s_nop 0
	v_add_f32_e32 v0, 1.0, v0
	v_rcp_f32_e32 v11, v0
	s_nop 0
	v_pk_mul_f32 v[10:11], v[2:3], v[10:11]
	v_lshlrev_b32_e32 v2, 16, v38
	v_and_b32_e32 v3, 0xffff0000, v38
	v_pk_fma_f32 v[2:3], v[12:13], v[2:3], v[4:5]
	s_nop 0
	v_pk_fma_f32 v[2:3], v[28:29], v[14:15], v[2:3]
	s_nop 0
	v_mul_f32_e32 v0, 0xbfb8aa3b, v2
	v_exp_f32_e32 v0, v0
	s_nop 0
	v_add_f32_e32 v0, 1.0, v0
	v_rcp_f32_e32 v4, v0
	v_mul_f32_e32 v0, 0xbfb8aa3b, v3
	v_exp_f32_e32 v0, v0
	s_nop 0
	v_add_f32_e32 v0, 1.0, v0
	v_rcp_f32_e32 v5, v0
	v_lshrrev_b32_e32 v0, 1, v99
	v_and_b32_e32 v0, 24, v0
	v_lshl_add_u64 v[24:25], v[20:21], 0, v[0:1]
	v_pk_mul_f32 v[12:13], v[2:3], v[4:5]
	v_cvt_pk_bf16_f32 v2, v6, v7
	v_cvt_pk_bf16_f32 v3, v8, v9
	v_cvt_pk_bf16_f32 v4, v10, v11
	v_cvt_pk_bf16_f32 v5, v12, v13
	ds_write_b128 v76, v[2:5] offset:48
	global_store_dwordx4 v[74:75], v[2:5], off offset:48
	s_waitcnt lgkmcnt(0)
	s_barrier
	s_nop 1
	v_bfe_u32 v2, v188, 2, 2
	v_lshlrev_b32_e32 v4, 2, v188
	v_or_b32_e32 v2, v0, v2
	v_and_b32_e32 v4, 12, v4
	v_add_u32_e32 v3, s35, v26
	v_lshlrev_b32_e32 v27, 1, v4
	v_mul_u32_u24_e32 v28, 0x110, v2
	v_add3_u32 v16, v3, v27, v28
	v_and_b32_e32 v0, 48, v99
	ds_read_b64_tr_b16 v[2:3], v16
	ds_read_b64_tr_b16 v[4:5], v16 offset:1088
	ds_read_b64_tr_b16 v[6:7], v16 offset:8704
	ds_read_b64_tr_b16 v[8:9], v16 offset:9792
	ds_read_b64_tr_b16 v[10:11], v16 offset:17408
	ds_read_b64_tr_b16 v[12:13], v16 offset:18496
	ds_read_b64_tr_b16 v[14:15], v16 offset:26112
	ds_read_b64_tr_b16 v[16:17], v16 offset:27200
	v_lshl_add_u64 v[22:23], v[18:19], 0, v[0:1]
	v_add3_u32 v0, 0, v27, v28
	ds_read_b64_tr_b16 v[30:31], v0
	ds_read_b64_tr_b16 v[32:33], v0 offset:1088
	ds_read_b64_tr_b16 v[34:35], v0 offset:8704
	ds_read_b64_tr_b16 v[36:37], v0 offset:9792
	ds_read_b64_tr_b16 v[166:167], v0 offset:17408
	ds_read_b64_tr_b16 v[168:169], v0 offset:18496
	ds_read_b64_tr_b16 v[170:171], v0 offset:26112
	ds_read_b64_tr_b16 v[172:173], v0 offset:27200
	v_lshl_add_u64 v[18:19], v[24:25], 0, s[4:5]
	s_waitcnt lgkmcnt(6)
	v_mfma_f32_16x16x32_bf16 v[30:33], v[30:33], v[2:5], 0
	s_waitcnt lgkmcnt(4)
	v_mfma_f32_16x16x32_bf16 v[30:33], v[34:37], v[6:9], v[30:33]
	s_waitcnt lgkmcnt(2)
	v_mfma_f32_16x16x32_bf16 v[30:33], v[166:169], v[10:13], v[30:33]
	s_waitcnt lgkmcnt(0)
	v_mfma_f32_16x16x32_bf16 v[30:33], v[170:173], v[14:17], v[30:33]
	ds_read_b64_tr_b16 v[150:151], v0 offset:32
	ds_read_b64_tr_b16 v[152:153], v0 offset:1120
	ds_read_b64_tr_b16 v[154:155], v0 offset:8736
	ds_read_b64_tr_b16 v[156:157], v0 offset:9824
	ds_read_b64_tr_b16 v[158:159], v0 offset:17440
	ds_read_b64_tr_b16 v[160:161], v0 offset:18528
	ds_read_b64_tr_b16 v[162:163], v0 offset:26144
	ds_read_b64_tr_b16 v[164:165], v0 offset:27232
	s_nop 1
	v_cvt_pk_bf16_f32 v20, v30, v31
	v_cvt_pk_bf16_f32 v21, v32, v33
	global_store_dwordx2 v[18:19], v[20:21], off
	s_waitcnt lgkmcnt(6)
	v_mfma_f32_16x16x32_bf16 v[150:153], v[150:153], v[2:5], 0
	s_waitcnt lgkmcnt(4)
	v_mfma_f32_16x16x32_bf16 v[150:153], v[154:157], v[6:9], v[150:153]
	s_waitcnt lgkmcnt(2)
	v_mfma_f32_16x16x32_bf16 v[150:153], v[158:161], v[10:13], v[150:153]
	s_waitcnt lgkmcnt(0)
	v_mfma_f32_16x16x32_bf16 v[150:153], v[162:165], v[14:17], v[150:153]
	ds_read_b64_tr_b16 v[30:31], v0 offset:64
	ds_read_b64_tr_b16 v[32:33], v0 offset:1152
	ds_read_b64_tr_b16 v[34:35], v0 offset:8768
	ds_read_b64_tr_b16 v[36:37], v0 offset:9856
	ds_read_b64_tr_b16 v[166:167], v0 offset:17472
	ds_read_b64_tr_b16 v[168:169], v0 offset:18560
	ds_read_b64_tr_b16 v[170:171], v0 offset:26176
	ds_read_b64_tr_b16 v[172:173], v0 offset:27264
	s_nop 1
	v_cvt_pk_bf16_f32 v20, v150, v151
	v_cvt_pk_bf16_f32 v21, v152, v153
	global_store_dwordx2 v[18:19], v[20:21], off offset:32
	s_waitcnt lgkmcnt(6)
	v_mfma_f32_16x16x32_bf16 v[30:33], v[30:33], v[2:5], 0
	s_waitcnt lgkmcnt(4)
	v_mfma_f32_16x16x32_bf16 v[30:33], v[34:37], v[6:9], v[30:33]
	s_waitcnt lgkmcnt(2)
	v_mfma_f32_16x16x32_bf16 v[30:33], v[166:169], v[10:13], v[30:33]
	s_waitcnt lgkmcnt(0)
	v_mfma_f32_16x16x32_bf16 v[30:33], v[170:173], v[14:17], v[30:33]
	ds_read_b64_tr_b16 v[150:151], v0 offset:96
	ds_read_b64_tr_b16 v[152:153], v0 offset:1184
	ds_read_b64_tr_b16 v[154:155], v0 offset:8800
	ds_read_b64_tr_b16 v[156:157], v0 offset:9888
	ds_read_b64_tr_b16 v[158:159], v0 offset:17504
	ds_read_b64_tr_b16 v[160:161], v0 offset:18592
	ds_read_b64_tr_b16 v[162:163], v0 offset:26208
	ds_read_b64_tr_b16 v[164:165], v0 offset:27296
	s_nop 1
	v_cvt_pk_bf16_f32 v20, v30, v31
	v_cvt_pk_bf16_f32 v21, v32, v33
	global_store_dwordx2 v[18:19], v[20:21], off offset:64
	s_waitcnt lgkmcnt(6)
	v_mfma_f32_16x16x32_bf16 v[150:153], v[150:153], v[2:5], 0
	s_waitcnt lgkmcnt(4)
	v_mfma_f32_16x16x32_bf16 v[150:153], v[154:157], v[6:9], v[150:153]
	s_waitcnt lgkmcnt(2)
	v_mfma_f32_16x16x32_bf16 v[150:153], v[158:161], v[10:13], v[150:153]
	s_waitcnt lgkmcnt(0)
	v_mfma_f32_16x16x32_bf16 v[150:153], v[162:165], v[14:17], v[150:153]
	ds_read_b64_tr_b16 v[30:31], v0 offset:128
	ds_read_b64_tr_b16 v[32:33], v0 offset:1216
	ds_read_b64_tr_b16 v[34:35], v0 offset:8832
	ds_read_b64_tr_b16 v[36:37], v0 offset:9920
	ds_read_b64_tr_b16 v[166:167], v0 offset:17536
	ds_read_b64_tr_b16 v[168:169], v0 offset:18624
	ds_read_b64_tr_b16 v[170:171], v0 offset:26240
	ds_read_b64_tr_b16 v[172:173], v0 offset:27328
	s_nop 1
	v_cvt_pk_bf16_f32 v20, v150, v151
	v_cvt_pk_bf16_f32 v21, v152, v153
	global_store_dwordx2 v[18:19], v[20:21], off offset:96
	s_waitcnt lgkmcnt(6)
	v_mfma_f32_16x16x32_bf16 v[30:33], v[30:33], v[2:5], 0
	s_waitcnt lgkmcnt(4)
	v_mfma_f32_16x16x32_bf16 v[30:33], v[34:37], v[6:9], v[30:33]
	s_waitcnt lgkmcnt(2)
	v_mfma_f32_16x16x32_bf16 v[30:33], v[166:169], v[10:13], v[30:33]
	s_waitcnt lgkmcnt(0)
	v_mfma_f32_16x16x32_bf16 v[30:33], v[170:173], v[14:17], v[30:33]
	ds_read_b64_tr_b16 v[150:151], v0 offset:160
	ds_read_b64_tr_b16 v[152:153], v0 offset:1248
	ds_read_b64_tr_b16 v[154:155], v0 offset:8864
	ds_read_b64_tr_b16 v[156:157], v0 offset:9952
	ds_read_b64_tr_b16 v[158:159], v0 offset:17568
	ds_read_b64_tr_b16 v[160:161], v0 offset:18656
	ds_read_b64_tr_b16 v[162:163], v0 offset:26272
	ds_read_b64_tr_b16 v[164:165], v0 offset:27360
	s_nop 1
	v_cvt_pk_bf16_f32 v20, v30, v31
	v_cvt_pk_bf16_f32 v21, v32, v33
	global_store_dwordx2 v[18:19], v[20:21], off offset:128
	s_waitcnt lgkmcnt(6)
	v_mfma_f32_16x16x32_bf16 v[150:153], v[150:153], v[2:5], 0
	s_waitcnt lgkmcnt(4)
	v_mfma_f32_16x16x32_bf16 v[150:153], v[154:157], v[6:9], v[150:153]
	s_waitcnt lgkmcnt(2)
	v_mfma_f32_16x16x32_bf16 v[150:153], v[158:161], v[10:13], v[150:153]
	s_waitcnt lgkmcnt(0)
	v_mfma_f32_16x16x32_bf16 v[150:153], v[162:165], v[14:17], v[150:153]
	ds_read_b64_tr_b16 v[30:31], v0 offset:192
	ds_read_b64_tr_b16 v[32:33], v0 offset:1280
	ds_read_b64_tr_b16 v[34:35], v0 offset:8896
	ds_read_b64_tr_b16 v[36:37], v0 offset:9984
	ds_read_b64_tr_b16 v[166:167], v0 offset:17600
	ds_read_b64_tr_b16 v[168:169], v0 offset:18688
	ds_read_b64_tr_b16 v[170:171], v0 offset:26304
	ds_read_b64_tr_b16 v[172:173], v0 offset:27392
	s_nop 1
	v_cvt_pk_bf16_f32 v20, v150, v151
	v_cvt_pk_bf16_f32 v21, v152, v153
	global_store_dwordx2 v[18:19], v[20:21], off offset:160
	s_waitcnt lgkmcnt(6)
	v_mfma_f32_16x16x32_bf16 v[30:33], v[30:33], v[2:5], 0
	s_waitcnt lgkmcnt(4)
	v_mfma_f32_16x16x32_bf16 v[30:33], v[34:37], v[6:9], v[30:33]
	s_waitcnt lgkmcnt(2)
	v_mfma_f32_16x16x32_bf16 v[30:33], v[166:169], v[10:13], v[30:33]
	s_waitcnt lgkmcnt(0)
	v_mfma_f32_16x16x32_bf16 v[30:33], v[170:173], v[14:17], v[30:33]
	ds_read_b64_tr_b16 v[150:151], v0 offset:224
	ds_read_b64_tr_b16 v[152:153], v0 offset:1312
	ds_read_b64_tr_b16 v[154:155], v0 offset:8928
	ds_read_b64_tr_b16 v[156:157], v0 offset:10016
	ds_read_b64_tr_b16 v[158:159], v0 offset:17632
	ds_read_b64_tr_b16 v[160:161], v0 offset:18720
	ds_read_b64_tr_b16 v[162:163], v0 offset:26336
	ds_read_b64_tr_b16 v[164:165], v0 offset:27424
	s_nop 1
	v_cvt_pk_bf16_f32 v20, v30, v31
	v_cvt_pk_bf16_f32 v21, v32, v33
	global_store_dwordx2 v[18:19], v[20:21], off offset:192
	v_add_u32_e32 v0, v0, v26
	s_waitcnt lgkmcnt(6)
	v_mfma_f32_16x16x32_bf16 v[150:153], v[150:153], v[2:5], 0
	s_waitcnt lgkmcnt(4)
	v_mfma_f32_16x16x32_bf16 v[150:153], v[154:157], v[6:9], v[150:153]
	s_waitcnt lgkmcnt(2)
	v_mfma_f32_16x16x32_bf16 v[150:153], v[158:161], v[10:13], v[150:153]
	s_waitcnt lgkmcnt(0)
	v_mfma_f32_16x16x32_bf16 v[150:153], v[162:165], v[14:17], v[150:153]
	s_nop 7
	v_cvt_pk_bf16_f32 v20, v150, v151
	v_cvt_pk_bf16_f32 v21, v152, v153
	global_store_dwordx2 v[18:19], v[20:21], off offset:224
	ds_read_b64_tr_b16 v[18:19], v0
	ds_read_b64_tr_b16 v[20:21], v0 offset:1088
	v_mov_b64_e32 v[32:33], s[26:27]
	v_mov_b64_e32 v[30:31], s[24:25]
	ds_read_b64_tr_b16 v[34:35], v0 offset:8704
	ds_read_b64_tr_b16 v[36:37], v0 offset:9792
	s_waitcnt lgkmcnt(2)
	v_mfma_f32_16x16x32_bf16 v[18:21], v[18:21], v[30:33], 0
	s_waitcnt lgkmcnt(0)
	v_mfma_f32_16x16x32_bf16 v[18:21], v[34:37], v[30:33], v[18:21]
	ds_read_b64_tr_b16 v[34:35], v0 offset:17408
	ds_read_b64_tr_b16 v[36:37], v0 offset:18496
	s_waitcnt lgkmcnt(0)
	v_mfma_f32_16x16x32_bf16 v[18:21], v[34:37], v[30:33], v[18:21]
	ds_read_b64_tr_b16 v[34:35], v0 offset:26112
	ds_read_b64_tr_b16 v[36:37], v0 offset:27200
	s_waitcnt lgkmcnt(0)
	v_mfma_f32_16x16x32_bf16 v[18:21], v[34:37], v[30:33], v[18:21]
	s_and_saveexec_b64 s[4:5], vcc
	s_cbranch_execz .LBB0_923
	s_lshl_b64 s[8:9], s[6:7], 9
	v_lshl_add_u64 v[30:31], v[22:23], 0, s[8:9]
	s_nop 3
	global_store_dwordx4 v[30:31], v[18:21], off

.LBB0_925:
	s_or_b64 exec, exec, s[8:9]
	v_add3_u32 v0, s34, v27, v28
	ds_read_b64_tr_b16 v[28:29], v0
	ds_read_b64_tr_b16 v[30:31], v0 offset:1088
	ds_read_b64_tr_b16 v[32:33], v0 offset:8704
	ds_read_b64_tr_b16 v[34:35], v0 offset:9792
	s_and_b64 s[6:7], s[56:57], exec
	s_cselect_b32 s6, 1, 19
	s_waitcnt lgkmcnt(2)
	v_mfma_f32_16x16x32_bf16 v[28:31], v[28:31], v[2:5], 0
	s_sub_i32 s7, s10, s30
	s_add_i32 s6, s7, s6
	s_addk_i32 s6, 0x48
	s_waitcnt lgkmcnt(0)
	v_mfma_f32_16x16x32_bf16 v[28:31], v[32:35], v[6:9], v[28:31]
	ds_read_b64_tr_b16 v[32:33], v0 offset:17408
	ds_read_b64_tr_b16 v[34:35], v0 offset:18496
	s_ashr_i32 s7, s6, 31
	s_lshl_b64 s[8:9], s[6:7], 15
	s_waitcnt lgkmcnt(0)
	v_mfma_f32_16x16x32_bf16 v[28:31], v[32:35], v[10:13], v[28:31]
	ds_read_b64_tr_b16 v[32:33], v0 offset:26112
	ds_read_b64_tr_b16 v[34:35], v0 offset:27200
	v_lshl_add_u64 v[18:19], v[24:25], 0, s[8:9]
	s_mov_b32 s25, s24
	s_waitcnt lgkmcnt(0)
	v_mfma_f32_16x16x32_bf16 v[28:31], v[32:35], v[14:17], v[28:31]
	s_mov_b32 s26, s24
	s_mov_b32 s27, s24
	s_nop 5
	v_cvt_pk_bf16_f32 v20, v28, v29
	v_cvt_pk_bf16_f32 v21, v30, v31
	global_store_dwordx2 v[18:19], v[20:21], off
	ds_read_b64_tr_b16 v[28:29], v0 offset:32
	ds_read_b64_tr_b16 v[30:31], v0 offset:1120
	ds_read_b64_tr_b16 v[32:33], v0 offset:8736
	ds_read_b64_tr_b16 v[34:35], v0 offset:9824
	ds_read_b64_tr_b16 v[166:167], v0 offset:17440
	ds_read_b64_tr_b16 v[168:169], v0 offset:18528
	ds_read_b64_tr_b16 v[170:171], v0 offset:26144
	ds_read_b64_tr_b16 v[172:173], v0 offset:27232
	s_waitcnt lgkmcnt(6)
	v_mfma_f32_16x16x32_bf16 v[28:31], v[28:31], v[2:5], 0
	s_waitcnt lgkmcnt(4)
	v_mfma_f32_16x16x32_bf16 v[28:31], v[32:35], v[6:9], v[28:31]
	s_waitcnt lgkmcnt(2)
	v_mfma_f32_16x16x32_bf16 v[28:31], v[166:169], v[10:13], v[28:31]
	s_waitcnt lgkmcnt(0)
	v_mfma_f32_16x16x32_bf16 v[28:31], v[170:173], v[14:17], v[28:31]
	ds_read_b64_tr_b16 v[150:151], v0 offset:64
	ds_read_b64_tr_b16 v[152:153], v0 offset:1152
	ds_read_b64_tr_b16 v[154:155], v0 offset:8768
	ds_read_b64_tr_b16 v[156:157], v0 offset:9856
	ds_read_b64_tr_b16 v[158:159], v0 offset:17472
	ds_read_b64_tr_b16 v[160:161], v0 offset:18560
	ds_read_b64_tr_b16 v[162:163], v0 offset:26176
	ds_read_b64_tr_b16 v[164:165], v0 offset:27264
	s_nop 1
	v_cvt_pk_bf16_f32 v20, v28, v29
	v_cvt_pk_bf16_f32 v21, v30, v31
	global_store_dwordx2 v[18:19], v[20:21], off offset:32
	s_waitcnt lgkmcnt(6)
	v_mfma_f32_16x16x32_bf16 v[150:153], v[150:153], v[2:5], 0
	s_waitcnt lgkmcnt(4)
	v_mfma_f32_16x16x32_bf16 v[150:153], v[154:157], v[6:9], v[150:153]
	s_waitcnt lgkmcnt(2)
	v_mfma_f32_16x16x32_bf16 v[150:153], v[158:161], v[10:13], v[150:153]
	s_waitcnt lgkmcnt(0)
	v_mfma_f32_16x16x32_bf16 v[150:153], v[162:165], v[14:17], v[150:153]
	ds_read_b64_tr_b16 v[28:29], v0 offset:96
	ds_read_b64_tr_b16 v[30:31], v0 offset:1184
	ds_read_b64_tr_b16 v[32:33], v0 offset:8800
	ds_read_b64_tr_b16 v[34:35], v0 offset:9888
	ds_read_b64_tr_b16 v[166:167], v0 offset:17504
	ds_read_b64_tr_b16 v[168:169], v0 offset:18592
	ds_read_b64_tr_b16 v[170:171], v0 offset:26208
	ds_read_b64_tr_b16 v[172:173], v0 offset:27296
	s_nop 1
	v_cvt_pk_bf16_f32 v20, v150, v151
	v_cvt_pk_bf16_f32 v21, v152, v153
	global_store_dwordx2 v[18:19], v[20:21], off offset:64
	s_waitcnt lgkmcnt(6)
	v_mfma_f32_16x16x32_bf16 v[28:31], v[28:31], v[2:5], 0
	s_waitcnt lgkmcnt(4)
	v_mfma_f32_16x16x32_bf16 v[28:31], v[32:35], v[6:9], v[28:31]
	s_waitcnt lgkmcnt(2)
	v_mfma_f32_16x16x32_bf16 v[28:31], v[166:169], v[10:13], v[28:31]
	s_waitcnt lgkmcnt(0)
	v_mfma_f32_16x16x32_bf16 v[28:31], v[170:173], v[14:17], v[28:31]
	ds_read_b64_tr_b16 v[150:151], v0 offset:128
	ds_read_b64_tr_b16 v[152:153], v0 offset:1216
	ds_read_b64_tr_b16 v[154:155], v0 offset:8832
	ds_read_b64_tr_b16 v[156:157], v0 offset:9920
	ds_read_b64_tr_b16 v[158:159], v0 offset:17536
	ds_read_b64_tr_b16 v[160:161], v0 offset:18624
	ds_read_b64_tr_b16 v[162:163], v0 offset:26240
	ds_read_b64_tr_b16 v[164:165], v0 offset:27328
	s_nop 1
	v_cvt_pk_bf16_f32 v20, v28, v29
	v_cvt_pk_bf16_f32 v21, v30, v31
	global_store_dwordx2 v[18:19], v[20:21], off offset:96
	s_waitcnt lgkmcnt(6)
	v_mfma_f32_16x16x32_bf16 v[150:153], v[150:153], v[2:5], 0
	s_waitcnt lgkmcnt(4)
	v_mfma_f32_16x16x32_bf16 v[150:153], v[154:157], v[6:9], v[150:153]
	s_waitcnt lgkmcnt(2)
	v_mfma_f32_16x16x32_bf16 v[150:153], v[158:161], v[10:13], v[150:153]
	s_waitcnt lgkmcnt(0)
	v_mfma_f32_16x16x32_bf16 v[150:153], v[162:165], v[14:17], v[150:153]
	ds_read_b64_tr_b16 v[28:29], v0 offset:160
	ds_read_b64_tr_b16 v[30:31], v0 offset:1248
	ds_read_b64_tr_b16 v[32:33], v0 offset:8864
	ds_read_b64_tr_b16 v[34:35], v0 offset:9952
	ds_read_b64_tr_b16 v[166:167], v0 offset:17568
	ds_read_b64_tr_b16 v[168:169], v0 offset:18656
	ds_read_b64_tr_b16 v[170:171], v0 offset:26272
	ds_read_b64_tr_b16 v[172:173], v0 offset:27360
	s_nop 1
	v_cvt_pk_bf16_f32 v20, v150, v151
	v_cvt_pk_bf16_f32 v21, v152, v153
	global_store_dwordx2 v[18:19], v[20:21], off offset:128
	s_waitcnt lgkmcnt(6)
	v_mfma_f32_16x16x32_bf16 v[28:31], v[28:31], v[2:5], 0
	s_waitcnt lgkmcnt(4)
	v_mfma_f32_16x16x32_bf16 v[28:31], v[32:35], v[6:9], v[28:31]
	s_waitcnt lgkmcnt(2)
	v_mfma_f32_16x16x32_bf16 v[28:31], v[166:169], v[10:13], v[28:31]
	s_waitcnt lgkmcnt(0)
	v_mfma_f32_16x16x32_bf16 v[28:31], v[170:173], v[14:17], v[28:31]
	ds_read_b64_tr_b16 v[150:151], v0 offset:192
	ds_read_b64_tr_b16 v[152:153], v0 offset:1280
	ds_read_b64_tr_b16 v[154:155], v0 offset:8896
	ds_read_b64_tr_b16 v[156:157], v0 offset:9984
	ds_read_b64_tr_b16 v[158:159], v0 offset:17600
	ds_read_b64_tr_b16 v[160:161], v0 offset:18688
	ds_read_b64_tr_b16 v[162:163], v0 offset:26304
	ds_read_b64_tr_b16 v[164:165], v0 offset:27392
	s_nop 1
	v_cvt_pk_bf16_f32 v20, v28, v29
	v_cvt_pk_bf16_f32 v21, v30, v31
	global_store_dwordx2 v[18:19], v[20:21], off offset:160
	s_waitcnt lgkmcnt(6)
	v_mfma_f32_16x16x32_bf16 v[150:153], v[150:153], v[2:5], 0
	s_waitcnt lgkmcnt(4)
	v_mfma_f32_16x16x32_bf16 v[150:153], v[154:157], v[6:9], v[150:153]
	s_waitcnt lgkmcnt(2)
	v_mfma_f32_16x16x32_bf16 v[150:153], v[158:161], v[10:13], v[150:153]
	s_waitcnt lgkmcnt(0)
	v_mfma_f32_16x16x32_bf16 v[150:153], v[162:165], v[14:17], v[150:153]
	s_nop 7
	v_cvt_pk_bf16_f32 v20, v150, v151
	v_cvt_pk_bf16_f32 v21, v152, v153
	global_store_dwordx2 v[18:19], v[20:21], off offset:192
	ds_read_b64_tr_b16 v[28:29], v0 offset:224
	ds_read_b64_tr_b16 v[30:31], v0 offset:1312
	s_waitcnt lgkmcnt(0)
	v_mfma_f32_16x16x32_bf16 v[2:5], v[28:31], v[2:5], 0
	ds_read_b64_tr_b16 v[28:29], v0 offset:8928
	ds_read_b64_tr_b16 v[30:31], v0 offset:10016
	s_waitcnt lgkmcnt(0)
	v_mfma_f32_16x16x32_bf16 v[2:5], v[28:31], v[6:9], v[2:5]
	ds_read_b64_tr_b16 v[6:7], v0 offset:17632
	ds_read_b64_tr_b16 v[8:9], v0 offset:18720
	s_waitcnt lgkmcnt(0)
	v_mfma_f32_16x16x32_bf16 v[2:5], v[6:9], v[10:13], v[2:5]
	ds_read_b64_tr_b16 v[6:7], v0 offset:26336
	ds_read_b64_tr_b16 v[8:9], v0 offset:27424
	v_add_u32_e32 v0, v0, v26
	s_waitcnt lgkmcnt(0)
	v_mfma_f32_16x16x32_bf16 v[2:5], v[6:9], v[14:17], v[2:5]
	v_mov_b64_e32 v[6:7], s[24:25]
	v_mov_b64_e32 v[8:9], s[26:27]
	s_nop 5
	v_cvt_pk_bf16_f32 v2, v2, v3
	v_cvt_pk_bf16_f32 v3, v4, v5
	global_store_dwordx2 v[18:19], v[2:3], off offset:224
	ds_read_b64_tr_b16 v[2:3], v0
	ds_read_b64_tr_b16 v[4:5], v0 offset:1088
	ds_read_b64_tr_b16 v[10:11], v0 offset:8704
	ds_read_b64_tr_b16 v[12:13], v0 offset:9792
	s_waitcnt lgkmcnt(2)
	v_mfma_f32_16x16x32_bf16 v[2:5], v[2:5], v[6:9], 0
	s_waitcnt lgkmcnt(0)
	v_mfma_f32_16x16x32_bf16 v[2:5], v[10:13], v[6:9], v[2:5]
	ds_read_b64_tr_b16 v[10:11], v0 offset:17408
	ds_read_b64_tr_b16 v[12:13], v0 offset:18496
	s_waitcnt lgkmcnt(0)
	v_mfma_f32_16x16x32_bf16 v[2:5], v[10:13], v[6:9], v[2:5]
	ds_read_b64_tr_b16 v[10:11], v0 offset:26112
	ds_read_b64_tr_b16 v[12:13], v0 offset:27200
	s_waitcnt lgkmcnt(0)
	v_mfma_f32_16x16x32_bf16 v[2:5], v[10:13], v[6:9], v[2:5]
	s_and_saveexec_b64 s[8:9], vcc
	s_cbranch_execz .LBB0_927
	s_lshl_b64 s[10:11], s[6:7], 9
	v_lshl_add_u64 v[6:7], v[22:23], 0, s[10:11]
	s_nop 3
	global_store_dwordx4 v[6:7], v[2:5], off
